# P1 epilogue stores carry the nt (streaming) hint so the 671 MB of projection outputs disturb the K-loop's L2-resident A/B tiles less
# speedup vs baseline: 1.0011x; 1.0011x over previous
; __device__ __forceinline__ unsigned cvt_pk_bf16(float lo, float hi) { unsigned r; asm volatile("v_cvt_pk_bf16_f32 %0, %1, %2" : "=v"(r) : "v"(lo), "v"(hi)); return r; }
; __device__ __forceinline__ float silu_f(float x) { return x * __builtin_amdgcn_rcpf(1.f + __expf(-x)); }
;     __device__ __forceinline__ void operator()(const f32x4 (&acc)[2][2][4][2], const pg8::Unit& u, int wr, int wc, int fr, int fq) const {
;     ...
;         } else {
;             const bool act = (sec == 3 || sec == 7);
;             const int col0 = 256 * half + 64 * wc + 8 * fq;
; #pragma unroll
;             for (int ai = 0; ai < 2; ++ai)
; #pragma unroll
;                 for (int m = 0; m < 4; ++m) {
;                     bf16_t* rowp = base + (size_t)(row0 + ai * 128 + m * 16) * 512 + col0;
; #pragma unroll
;                     for (int bj = 0; bj < 2; ++bj) { f32x4 v0 = acc[ai][bj][m][0], v1 = acc[ai][bj][m][1];
;                         if (act) { v0 = (f32x4){silu_f(v0[0]), silu_f(v0[1]), silu_f(v0[2]), silu_f(v0[3])}; v1 = (f32x4){silu_f(v1[0]), silu_f(v1[1]), silu_f(v1[2]), silu_f(v1[3])}; }
;                         u32x4 w; w.x = cvt_pk_bf16(v0[0], v0[1]); w.y = cvt_pk_bf16(v0[2], v0[3]); w.z = cvt_pk_bf16(v1[0], v1[1]); w.w = cvt_pk_bf16(v1[2], v1[3]);
;                         *(u32x4*)(rowp + 32 * bj) = w; }
;                 }
.LBB0_168:
	s_and_b32 s4, s41, 0x7ffffffe
	s_cmp_lg_u32 s4, 4
	s_mov_b64 s[4:5], -1
	s_cbranch_scc0 .LBB0_202
	s_and_b32 s4, s41, 0x7ffffffb
	v_lshlrev_b32_e32 v130, 1, v182
	v_lshl_or_b32 v154, s27, 9, v130
	v_and_b32_e32 v131, 1, v172
	v_lshl_add_u32 v154, v131, 6, v154
	v_and_b32_e32 v132, -2, v172
	v_ashrrev_i32_e32 v173, 31, v172
	v_ashrrev_i32_e32 v133, 31, v132
	v_lshlrev_b64 v[132:133], 10, v[132:133]
	v_lshl_add_u64 v[130:131], s[48:49], 0, v[154:155]
	v_lshl_add_u64 v[130:131], v[130:131], 0, v[132:133]
	s_mov_b32 vcc_lo, 0x55555555
	s_mov_b32 vcc_hi, 0x55555555
	s_cmp_lg_u32 s4, 3
	s_mov_b64 s[4:5], 0x4000
	s_cbranch_scc1 .Lp1e_plain
	v_mul_f32_e32 v224, 0xbfb8aa3b, v118
	v_mul_f32_e32 v225, 0xbfb8aa3b, v119
	v_mul_f32_e32 v226, 0xbfb8aa3b, v120
	v_mul_f32_e32 v227, 0xbfb8aa3b, v121
	v_mul_f32_e32 v228, 0xbfb8aa3b, v114
	v_mul_f32_e32 v229, 0xbfb8aa3b, v115
	v_mul_f32_e32 v230, 0xbfb8aa3b, v116
	v_mul_f32_e32 v231, 0xbfb8aa3b, v117
	v_exp_f32_e32 v224, v224
	v_exp_f32_e32 v225, v225
	v_exp_f32_e32 v226, v226
	v_exp_f32_e32 v227, v227
	v_exp_f32_e32 v228, v228
	v_exp_f32_e32 v229, v229
	v_exp_f32_e32 v230, v230
	v_exp_f32_e32 v231, v231
	v_add_f32_e32 v224, 1.0, v224
	v_add_f32_e32 v225, 1.0, v225
	v_add_f32_e32 v226, 1.0, v226
	v_add_f32_e32 v227, 1.0, v227
	v_add_f32_e32 v228, 1.0, v228
	v_add_f32_e32 v229, 1.0, v229
	v_add_f32_e32 v230, 1.0, v230
	v_add_f32_e32 v231, 1.0, v231
	v_rcp_f32_e32 v224, v224
	v_rcp_f32_e32 v225, v225
	v_rcp_f32_e32 v226, v226
	v_rcp_f32_e32 v227, v227
	v_rcp_f32_e32 v228, v228
	v_rcp_f32_e32 v229, v229
	v_rcp_f32_e32 v230, v230
	v_rcp_f32_e32 v231, v231
	v_pk_mul_f32 v[224:225], v[118:119], v[224:225]
	v_pk_mul_f32 v[226:227], v[120:121], v[226:227]
	v_pk_mul_f32 v[228:229], v[114:115], v[228:229]
	v_pk_mul_f32 v[230:231], v[116:117], v[230:231]
	v_cvt_pk_bf16_f32 v204, v224, v225
	v_cvt_pk_bf16_f32 v205, v226, v227
	v_cvt_pk_bf16_f32 v206, v228, v229
	v_cvt_pk_bf16_f32 v207, v230, v231
	v_mul_f32_e32 v132, 0xbfb8aa3b, v126
	v_mul_f32_e32 v133, 0xbfb8aa3b, v127
	v_mul_f32_e32 v134, 0xbfb8aa3b, v128
	v_mul_f32_e32 v135, 0xbfb8aa3b, v129
	v_mul_f32_e32 v136, 0xbfb8aa3b, v122
	v_mul_f32_e32 v137, 0xbfb8aa3b, v123
	v_mul_f32_e32 v138, 0xbfb8aa3b, v124
	v_mul_f32_e32 v139, 0xbfb8aa3b, v125
	v_exp_f32_e32 v132, v132
	v_exp_f32_e32 v133, v133
	v_exp_f32_e32 v134, v134
	v_exp_f32_e32 v135, v135
	v_exp_f32_e32 v136, v136
	v_exp_f32_e32 v137, v137
	v_exp_f32_e32 v138, v138
	v_exp_f32_e32 v139, v139
	v_add_f32_e32 v132, 1.0, v132
	v_add_f32_e32 v133, 1.0, v133
	v_add_f32_e32 v134, 1.0, v134
	v_add_f32_e32 v135, 1.0, v135
	v_add_f32_e32 v136, 1.0, v136
	v_add_f32_e32 v137, 1.0, v137
	v_add_f32_e32 v138, 1.0, v138
	v_add_f32_e32 v139, 1.0, v139
	v_rcp_f32_e32 v132, v132
	v_rcp_f32_e32 v133, v133
	v_rcp_f32_e32 v134, v134
	v_rcp_f32_e32 v135, v135
	v_rcp_f32_e32 v136, v136
	v_rcp_f32_e32 v137, v137
	v_rcp_f32_e32 v138, v138
	v_rcp_f32_e32 v139, v139
	v_pk_mul_f32 v[132:133], v[126:127], v[132:133]
	v_pk_mul_f32 v[134:135], v[128:129], v[134:135]
	v_pk_mul_f32 v[136:137], v[122:123], v[136:137]
	v_pk_mul_f32 v[138:139], v[124:125], v[138:139]
	v_cvt_pk_bf16_f32 v200, v132, v133
	v_cvt_pk_bf16_f32 v201, v134, v135
	v_cvt_pk_bf16_f32 v202, v136, v137
	v_cvt_pk_bf16_f32 v203, v138, v139
	v_cndmask_b32_dpp v208, v204, v200, vcc quad_perm:[1,0,3,2] row_mask:0xf bank_mask:0xf
	v_cndmask_b32_dpp v209, v205, v201, vcc quad_perm:[1,0,3,2] row_mask:0xf bank_mask:0xf
	v_cndmask_b32_dpp v210, v206, v202, vcc quad_perm:[1,0,3,2] row_mask:0xf bank_mask:0xf
	v_cndmask_b32_dpp v211, v207, v203, vcc quad_perm:[1,0,3,2] row_mask:0xf bank_mask:0xf
	s_not_b64 vcc, vcc
	v_cndmask_b32_dpp v212, v200, v204, vcc quad_perm:[1,0,3,2] row_mask:0xf bank_mask:0xf
	v_cndmask_b32_dpp v213, v201, v205, vcc quad_perm:[1,0,3,2] row_mask:0xf bank_mask:0xf
	v_cndmask_b32_dpp v214, v202, v206, vcc quad_perm:[1,0,3,2] row_mask:0xf bank_mask:0xf
	v_cndmask_b32_dpp v215, v203, v207, vcc quad_perm:[1,0,3,2] row_mask:0xf bank_mask:0xf
	s_not_b64 vcc, vcc
	global_store_dwordx4 v[130:131], v[208:211], off nt
	global_store_dwordx4 v[130:131], v[212:215], off offset:1024 nt
	v_lshl_add_u64 v[130:131], v[130:131], 0, s[4:5]
	v_mul_f32_e32 v224, 0xbfb8aa3b, v102
	v_mul_f32_e32 v225, 0xbfb8aa3b, v103
	v_mul_f32_e32 v226, 0xbfb8aa3b, v104
	v_mul_f32_e32 v227, 0xbfb8aa3b, v105
	v_mul_f32_e32 v228, 0xbfb8aa3b, v98
	v_mul_f32_e32 v229, 0xbfb8aa3b, v99
	v_mul_f32_e32 v230, 0xbfb8aa3b, v100
	v_mul_f32_e32 v231, 0xbfb8aa3b, v101
	v_exp_f32_e32 v224, v224
	v_exp_f32_e32 v225, v225
	v_exp_f32_e32 v226, v226
	v_exp_f32_e32 v227, v227
	v_exp_f32_e32 v228, v228
	v_exp_f32_e32 v229, v229
	v_exp_f32_e32 v230, v230
	v_exp_f32_e32 v231, v231
	v_add_f32_e32 v224, 1.0, v224
	v_add_f32_e32 v225, 1.0, v225
	v_add_f32_e32 v226, 1.0, v226
	v_add_f32_e32 v227, 1.0, v227
	v_add_f32_e32 v228, 1.0, v228
	v_add_f32_e32 v229, 1.0, v229
	v_add_f32_e32 v230, 1.0, v230
	v_add_f32_e32 v231, 1.0, v231
	v_rcp_f32_e32 v224, v224
	v_rcp_f32_e32 v225, v225
	v_rcp_f32_e32 v226, v226
	v_rcp_f32_e32 v227, v227
	v_rcp_f32_e32 v228, v228
	v_rcp_f32_e32 v229, v229
	v_rcp_f32_e32 v230, v230
	v_rcp_f32_e32 v231, v231
	v_pk_mul_f32 v[224:225], v[102:103], v[224:225]
	v_pk_mul_f32 v[226:227], v[104:105], v[226:227]
	v_pk_mul_f32 v[228:229], v[98:99], v[228:229]
	v_pk_mul_f32 v[230:231], v[100:101], v[230:231]
	v_cvt_pk_bf16_f32 v204, v224, v225
	v_cvt_pk_bf16_f32 v205, v226, v227
	v_cvt_pk_bf16_f32 v206, v228, v229
	v_cvt_pk_bf16_f32 v207, v230, v231
	v_mul_f32_e32 v132, 0xbfb8aa3b, v110
	v_mul_f32_e32 v133, 0xbfb8aa3b, v111
	v_mul_f32_e32 v134, 0xbfb8aa3b, v112
	v_mul_f32_e32 v135, 0xbfb8aa3b, v113
; __device__ __forceinline__ unsigned cvt_pk_bf16(float lo, float hi) { unsigned r; asm volatile("v_cvt_pk_bf16_f32 %0, %1, %2" : "=v"(r) : "v"(lo), "v"(hi)); return r; }
; __device__ __forceinline__ float silu_f(float x) { return x * __builtin_amdgcn_rcpf(1.f + __expf(-x)); }
;     __device__ __forceinline__ void operator()(const f32x4 (&acc)[2][2][4][2], const pg8::Unit& u, int wr, int wc, int fr, int fq) const {
;     ...
;         } else {
;             const bool act = (sec == 3 || sec == 7);
;             const int col0 = 256 * half + 64 * wc + 8 * fq;
; #pragma unroll
;             for (int ai = 0; ai < 2; ++ai)
; #pragma unroll
;                 for (int m = 0; m < 4; ++m) {
;                     bf16_t* rowp = base + (size_t)(row0 + ai * 128 + m * 16) * 512 + col0;
; #pragma unroll
;                     for (int bj = 0; bj < 2; ++bj) { f32x4 v0 = acc[ai][bj][m][0], v1 = acc[ai][bj][m][1];
;                         if (act) { v0 = (f32x4){silu_f(v0[0]), silu_f(v0[1]), silu_f(v0[2]), silu_f(v0[3])}; v1 = (f32x4){silu_f(v1[0]), silu_f(v1[1]), silu_f(v1[2]), silu_f(v1[3])}; }
;                         u32x4 w; w.x = cvt_pk_bf16(v0[0], v0[1]); w.y = cvt_pk_bf16(v0[2], v0[3]); w.z = cvt_pk_bf16(v1[0], v1[1]); w.w = cvt_pk_bf16(v1[2], v1[3]);
;                         *(u32x4*)(rowp + 32 * bj) = w; }
;                 }
	v_mul_f32_e32 v136, 0xbfb8aa3b, v106
	v_mul_f32_e32 v137, 0xbfb8aa3b, v107
	v_mul_f32_e32 v138, 0xbfb8aa3b, v108
	v_mul_f32_e32 v139, 0xbfb8aa3b, v109
	v_exp_f32_e32 v132, v132
	v_exp_f32_e32 v133, v133
	v_exp_f32_e32 v134, v134
	v_exp_f32_e32 v135, v135
	v_exp_f32_e32 v136, v136
	v_exp_f32_e32 v137, v137
	v_exp_f32_e32 v138, v138
	v_exp_f32_e32 v139, v139
	v_add_f32_e32 v132, 1.0, v132
	v_add_f32_e32 v133, 1.0, v133
	v_add_f32_e32 v134, 1.0, v134
	v_add_f32_e32 v135, 1.0, v135
	v_add_f32_e32 v136, 1.0, v136
	v_add_f32_e32 v137, 1.0, v137
	v_add_f32_e32 v138, 1.0, v138
	v_add_f32_e32 v139, 1.0, v139
	v_rcp_f32_e32 v132, v132
	v_rcp_f32_e32 v133, v133
	v_rcp_f32_e32 v134, v134
	v_rcp_f32_e32 v135, v135
	v_rcp_f32_e32 v136, v136
	v_rcp_f32_e32 v137, v137
	v_rcp_f32_e32 v138, v138
	v_rcp_f32_e32 v139, v139
	v_pk_mul_f32 v[132:133], v[110:111], v[132:133]
	v_pk_mul_f32 v[134:135], v[112:113], v[134:135]
	v_pk_mul_f32 v[136:137], v[106:107], v[136:137]
	v_pk_mul_f32 v[138:139], v[108:109], v[138:139]
	v_cvt_pk_bf16_f32 v200, v132, v133
	v_cvt_pk_bf16_f32 v201, v134, v135
	v_cvt_pk_bf16_f32 v202, v136, v137
	v_cvt_pk_bf16_f32 v203, v138, v139
	v_cndmask_b32_dpp v216, v204, v200, vcc quad_perm:[1,0,3,2] row_mask:0xf bank_mask:0xf
	v_cndmask_b32_dpp v217, v205, v201, vcc quad_perm:[1,0,3,2] row_mask:0xf bank_mask:0xf
	v_cndmask_b32_dpp v218, v206, v202, vcc quad_perm:[1,0,3,2] row_mask:0xf bank_mask:0xf
	v_cndmask_b32_dpp v219, v207, v203, vcc quad_perm:[1,0,3,2] row_mask:0xf bank_mask:0xf
	s_not_b64 vcc, vcc
	v_cndmask_b32_dpp v220, v200, v204, vcc quad_perm:[1,0,3,2] row_mask:0xf bank_mask:0xf
	v_cndmask_b32_dpp v221, v201, v205, vcc quad_perm:[1,0,3,2] row_mask:0xf bank_mask:0xf
	v_cndmask_b32_dpp v222, v202, v206, vcc quad_perm:[1,0,3,2] row_mask:0xf bank_mask:0xf
	v_cndmask_b32_dpp v223, v203, v207, vcc quad_perm:[1,0,3,2] row_mask:0xf bank_mask:0xf
	s_not_b64 vcc, vcc
	global_store_dwordx4 v[130:131], v[216:219], off nt
	global_store_dwordx4 v[130:131], v[220:223], off offset:1024 nt
	v_lshl_add_u64 v[130:131], v[130:131], 0, s[4:5]
	v_mul_f32_e32 v224, 0xbfb8aa3b, v86
	v_mul_f32_e32 v225, 0xbfb8aa3b, v87
	v_mul_f32_e32 v226, 0xbfb8aa3b, v88
	v_mul_f32_e32 v227, 0xbfb8aa3b, v89
	v_mul_f32_e32 v228, 0xbfb8aa3b, v82
	v_mul_f32_e32 v229, 0xbfb8aa3b, v83
	v_mul_f32_e32 v230, 0xbfb8aa3b, v84
	v_mul_f32_e32 v231, 0xbfb8aa3b, v85
	v_exp_f32_e32 v224, v224
	v_exp_f32_e32 v225, v225
	v_exp_f32_e32 v226, v226
	v_exp_f32_e32 v227, v227
	v_exp_f32_e32 v228, v228
	v_exp_f32_e32 v229, v229
	v_exp_f32_e32 v230, v230
	v_exp_f32_e32 v231, v231
	v_add_f32_e32 v224, 1.0, v224
	v_add_f32_e32 v225, 1.0, v225
	v_add_f32_e32 v226, 1.0, v226
	v_add_f32_e32 v227, 1.0, v227
	v_add_f32_e32 v228, 1.0, v228
	v_add_f32_e32 v229, 1.0, v229
	v_add_f32_e32 v230, 1.0, v230
	v_add_f32_e32 v231, 1.0, v231
	v_rcp_f32_e32 v224, v224
	v_rcp_f32_e32 v225, v225
	v_rcp_f32_e32 v226, v226
	v_rcp_f32_e32 v227, v227
	v_rcp_f32_e32 v228, v228
	v_rcp_f32_e32 v229, v229
	v_rcp_f32_e32 v230, v230
	v_rcp_f32_e32 v231, v231
	v_pk_mul_f32 v[224:225], v[86:87], v[224:225]
	v_pk_mul_f32 v[226:227], v[88:89], v[226:227]
	v_pk_mul_f32 v[228:229], v[82:83], v[228:229]
	v_pk_mul_f32 v[230:231], v[84:85], v[230:231]
	v_cvt_pk_bf16_f32 v204, v224, v225
	v_cvt_pk_bf16_f32 v205, v226, v227
	v_cvt_pk_bf16_f32 v206, v228, v229
	v_cvt_pk_bf16_f32 v207, v230, v231
	v_mul_f32_e32 v132, 0xbfb8aa3b, v94
	v_mul_f32_e32 v133, 0xbfb8aa3b, v95
	v_mul_f32_e32 v134, 0xbfb8aa3b, v96
	v_mul_f32_e32 v135, 0xbfb8aa3b, v97
	v_mul_f32_e32 v136, 0xbfb8aa3b, v90
	v_mul_f32_e32 v137, 0xbfb8aa3b, v91
	v_mul_f32_e32 v138, 0xbfb8aa3b, v92
	v_mul_f32_e32 v139, 0xbfb8aa3b, v93
	v_exp_f32_e32 v132, v132
	v_exp_f32_e32 v133, v133
	v_exp_f32_e32 v134, v134
	v_exp_f32_e32 v135, v135
	v_exp_f32_e32 v136, v136
	v_exp_f32_e32 v137, v137
	v_exp_f32_e32 v138, v138
	v_exp_f32_e32 v139, v139
	v_add_f32_e32 v132, 1.0, v132
	v_add_f32_e32 v133, 1.0, v133
	v_add_f32_e32 v134, 1.0, v134
	v_add_f32_e32 v135, 1.0, v135
	v_add_f32_e32 v136, 1.0, v136
	v_add_f32_e32 v137, 1.0, v137
	v_add_f32_e32 v138, 1.0, v138
	v_add_f32_e32 v139, 1.0, v139
	v_rcp_f32_e32 v132, v132
	v_rcp_f32_e32 v133, v133
	v_rcp_f32_e32 v134, v134
	v_rcp_f32_e32 v135, v135
	v_rcp_f32_e32 v136, v136
	v_rcp_f32_e32 v137, v137
	v_rcp_f32_e32 v138, v138
	v_rcp_f32_e32 v139, v139
	v_pk_mul_f32 v[132:133], v[94:95], v[132:133]
	v_pk_mul_f32 v[134:135], v[96:97], v[134:135]
	v_pk_mul_f32 v[136:137], v[90:91], v[136:137]
	v_pk_mul_f32 v[138:139], v[92:93], v[138:139]
	v_cvt_pk_bf16_f32 v200, v132, v133
	v_cvt_pk_bf16_f32 v201, v134, v135
	v_cvt_pk_bf16_f32 v202, v136, v137
	v_cvt_pk_bf16_f32 v203, v138, v139
	v_cndmask_b32_dpp v208, v204, v200, vcc quad_perm:[1,0,3,2] row_mask:0xf bank_mask:0xf
	v_cndmask_b32_dpp v209, v205, v201, vcc quad_perm:[1,0,3,2] row_mask:0xf bank_mask:0xf
	v_cndmask_b32_dpp v210, v206, v202, vcc quad_perm:[1,0,3,2] row_mask:0xf bank_mask:0xf
	v_cndmask_b32_dpp v211, v207, v203, vcc quad_perm:[1,0,3,2] row_mask:0xf bank_mask:0xf
	s_not_b64 vcc, vcc
	v_cndmask_b32_dpp v212, v200, v204, vcc quad_perm:[1,0,3,2] row_mask:0xf bank_mask:0xf
	v_cndmask_b32_dpp v213, v201, v205, vcc quad_perm:[1,0,3,2] row_mask:0xf bank_mask:0xf
	v_cndmask_b32_dpp v214, v202, v206, vcc quad_perm:[1,0,3,2] row_mask:0xf bank_mask:0xf
	v_cndmask_b32_dpp v215, v203, v207, vcc quad_perm:[1,0,3,2] row_mask:0xf bank_mask:0xf
	s_not_b64 vcc, vcc
	global_store_dwordx4 v[130:131], v[208:211], off nt
	global_store_dwordx4 v[130:131], v[212:215], off offset:1024 nt
	v_lshl_add_u64 v[130:131], v[130:131], 0, s[4:5]
	v_mul_f32_e32 v224, 0xbfb8aa3b, v70
	v_mul_f32_e32 v225, 0xbfb8aa3b, v71
; __device__ __forceinline__ unsigned cvt_pk_bf16(float lo, float hi) { unsigned r; asm volatile("v_cvt_pk_bf16_f32 %0, %1, %2" : "=v"(r) : "v"(lo), "v"(hi)); return r; }
; __device__ __forceinline__ float silu_f(float x) { return x * __builtin_amdgcn_rcpf(1.f + __expf(-x)); }
;     __device__ __forceinline__ void operator()(const f32x4 (&acc)[2][2][4][2], const pg8::Unit& u, int wr, int wc, int fr, int fq) const {
;     ...
;         } else {
;             const bool act = (sec == 3 || sec == 7);
;             const int col0 = 256 * half + 64 * wc + 8 * fq;
; #pragma unroll
;             for (int ai = 0; ai < 2; ++ai)
; #pragma unroll
;                 for (int m = 0; m < 4; ++m) {
;                     bf16_t* rowp = base + (size_t)(row0 + ai * 128 + m * 16) * 512 + col0;
; #pragma unroll
;                     for (int bj = 0; bj < 2; ++bj) { f32x4 v0 = acc[ai][bj][m][0], v1 = acc[ai][bj][m][1];
;                         if (act) { v0 = (f32x4){silu_f(v0[0]), silu_f(v0[1]), silu_f(v0[2]), silu_f(v0[3])}; v1 = (f32x4){silu_f(v1[0]), silu_f(v1[1]), silu_f(v1[2]), silu_f(v1[3])}; }
;                         u32x4 w; w.x = cvt_pk_bf16(v0[0], v0[1]); w.y = cvt_pk_bf16(v0[2], v0[3]); w.z = cvt_pk_bf16(v1[0], v1[1]); w.w = cvt_pk_bf16(v1[2], v1[3]);
;                         *(u32x4*)(rowp + 32 * bj) = w; }
;                 }
	v_mul_f32_e32 v226, 0xbfb8aa3b, v72
	v_mul_f32_e32 v227, 0xbfb8aa3b, v73
	v_mul_f32_e32 v228, 0xbfb8aa3b, v66
	v_mul_f32_e32 v229, 0xbfb8aa3b, v67
	v_mul_f32_e32 v230, 0xbfb8aa3b, v68
	v_mul_f32_e32 v231, 0xbfb8aa3b, v69
	v_exp_f32_e32 v224, v224
	v_exp_f32_e32 v225, v225
	v_exp_f32_e32 v226, v226
	v_exp_f32_e32 v227, v227
	v_exp_f32_e32 v228, v228
	v_exp_f32_e32 v229, v229
	v_exp_f32_e32 v230, v230
	v_exp_f32_e32 v231, v231
	v_add_f32_e32 v224, 1.0, v224
	v_add_f32_e32 v225, 1.0, v225
	v_add_f32_e32 v226, 1.0, v226
	v_add_f32_e32 v227, 1.0, v227
	v_add_f32_e32 v228, 1.0, v228
	v_add_f32_e32 v229, 1.0, v229
	v_add_f32_e32 v230, 1.0, v230
	v_add_f32_e32 v231, 1.0, v231
	v_rcp_f32_e32 v224, v224
	v_rcp_f32_e32 v225, v225
	v_rcp_f32_e32 v226, v226
	v_rcp_f32_e32 v227, v227
	v_rcp_f32_e32 v228, v228
	v_rcp_f32_e32 v229, v229
	v_rcp_f32_e32 v230, v230
	v_rcp_f32_e32 v231, v231
	v_pk_mul_f32 v[224:225], v[70:71], v[224:225]
	v_pk_mul_f32 v[226:227], v[72:73], v[226:227]
	v_pk_mul_f32 v[228:229], v[66:67], v[228:229]
	v_pk_mul_f32 v[230:231], v[68:69], v[230:231]
	v_cvt_pk_bf16_f32 v204, v224, v225
	v_cvt_pk_bf16_f32 v205, v226, v227
	v_cvt_pk_bf16_f32 v206, v228, v229
	v_cvt_pk_bf16_f32 v207, v230, v231
	v_mul_f32_e32 v132, 0xbfb8aa3b, v78
	v_mul_f32_e32 v133, 0xbfb8aa3b, v79
	v_mul_f32_e32 v134, 0xbfb8aa3b, v80
	v_mul_f32_e32 v135, 0xbfb8aa3b, v81
	v_mul_f32_e32 v136, 0xbfb8aa3b, v74
	v_mul_f32_e32 v137, 0xbfb8aa3b, v75
	v_mul_f32_e32 v138, 0xbfb8aa3b, v76
	v_mul_f32_e32 v139, 0xbfb8aa3b, v77
	v_exp_f32_e32 v132, v132
	v_exp_f32_e32 v133, v133
	v_exp_f32_e32 v134, v134
	v_exp_f32_e32 v135, v135
	v_exp_f32_e32 v136, v136
	v_exp_f32_e32 v137, v137
	v_exp_f32_e32 v138, v138
	v_exp_f32_e32 v139, v139
	v_add_f32_e32 v132, 1.0, v132
	v_add_f32_e32 v133, 1.0, v133
	v_add_f32_e32 v134, 1.0, v134
	v_add_f32_e32 v135, 1.0, v135
	v_add_f32_e32 v136, 1.0, v136
	v_add_f32_e32 v137, 1.0, v137
	v_add_f32_e32 v138, 1.0, v138
	v_add_f32_e32 v139, 1.0, v139
	v_rcp_f32_e32 v132, v132
	v_rcp_f32_e32 v133, v133
	v_rcp_f32_e32 v134, v134
	v_rcp_f32_e32 v135, v135
	v_rcp_f32_e32 v136, v136
	v_rcp_f32_e32 v137, v137
	v_rcp_f32_e32 v138, v138
	v_rcp_f32_e32 v139, v139
	v_pk_mul_f32 v[132:133], v[78:79], v[132:133]
	v_pk_mul_f32 v[134:135], v[80:81], v[134:135]
	v_pk_mul_f32 v[136:137], v[74:75], v[136:137]
	v_pk_mul_f32 v[138:139], v[76:77], v[138:139]
	v_cvt_pk_bf16_f32 v200, v132, v133
	v_cvt_pk_bf16_f32 v201, v134, v135
	v_cvt_pk_bf16_f32 v202, v136, v137
	v_cvt_pk_bf16_f32 v203, v138, v139
	v_cndmask_b32_dpp v216, v204, v200, vcc quad_perm:[1,0,3,2] row_mask:0xf bank_mask:0xf
	v_cndmask_b32_dpp v217, v205, v201, vcc quad_perm:[1,0,3,2] row_mask:0xf bank_mask:0xf
	v_cndmask_b32_dpp v218, v206, v202, vcc quad_perm:[1,0,3,2] row_mask:0xf bank_mask:0xf
	v_cndmask_b32_dpp v219, v207, v203, vcc quad_perm:[1,0,3,2] row_mask:0xf bank_mask:0xf
	s_not_b64 vcc, vcc
	v_cndmask_b32_dpp v220, v200, v204, vcc quad_perm:[1,0,3,2] row_mask:0xf bank_mask:0xf
	v_cndmask_b32_dpp v221, v201, v205, vcc quad_perm:[1,0,3,2] row_mask:0xf bank_mask:0xf
	v_cndmask_b32_dpp v222, v202, v206, vcc quad_perm:[1,0,3,2] row_mask:0xf bank_mask:0xf
	v_cndmask_b32_dpp v223, v203, v207, vcc quad_perm:[1,0,3,2] row_mask:0xf bank_mask:0xf
	s_not_b64 vcc, vcc
	global_store_dwordx4 v[130:131], v[216:219], off nt
	global_store_dwordx4 v[130:131], v[220:223], off offset:1024 nt
	s_mov_b64 s[4:5], 0x14000
	v_lshl_add_u64 v[130:131], v[130:131], 0, s[4:5]
	s_mov_b64 s[4:5], 0x4000
	v_mul_f32_e32 v224, 0xbfb8aa3b, v54
	v_mul_f32_e32 v225, 0xbfb8aa3b, v55
	v_mul_f32_e32 v226, 0xbfb8aa3b, v56
	v_mul_f32_e32 v227, 0xbfb8aa3b, v57
	v_mul_f32_e32 v228, 0xbfb8aa3b, v50
	v_mul_f32_e32 v229, 0xbfb8aa3b, v51
	v_mul_f32_e32 v230, 0xbfb8aa3b, v52
	v_mul_f32_e32 v231, 0xbfb8aa3b, v53
	v_exp_f32_e32 v224, v224
	v_exp_f32_e32 v225, v225
	v_exp_f32_e32 v226, v226
	v_exp_f32_e32 v227, v227
	v_exp_f32_e32 v228, v228
	v_exp_f32_e32 v229, v229
	v_exp_f32_e32 v230, v230
	v_exp_f32_e32 v231, v231
	v_add_f32_e32 v224, 1.0, v224
	v_add_f32_e32 v225, 1.0, v225
	v_add_f32_e32 v226, 1.0, v226
	v_add_f32_e32 v227, 1.0, v227
	v_add_f32_e32 v228, 1.0, v228
	v_add_f32_e32 v229, 1.0, v229
	v_add_f32_e32 v230, 1.0, v230
	v_add_f32_e32 v231, 1.0, v231
	v_rcp_f32_e32 v224, v224
	v_rcp_f32_e32 v225, v225
	v_rcp_f32_e32 v226, v226
	v_rcp_f32_e32 v227, v227
	v_rcp_f32_e32 v228, v228
	v_rcp_f32_e32 v229, v229
	v_rcp_f32_e32 v230, v230
	v_rcp_f32_e32 v231, v231
	v_pk_mul_f32 v[224:225], v[54:55], v[224:225]
	v_pk_mul_f32 v[226:227], v[56:57], v[226:227]
	v_pk_mul_f32 v[228:229], v[50:51], v[228:229]
	v_pk_mul_f32 v[230:231], v[52:53], v[230:231]
	v_cvt_pk_bf16_f32 v204, v224, v225
	v_cvt_pk_bf16_f32 v205, v226, v227
	v_cvt_pk_bf16_f32 v206, v228, v229
	v_cvt_pk_bf16_f32 v207, v230, v231
	v_mul_f32_e32 v132, 0xbfb8aa3b, v62
	v_mul_f32_e32 v133, 0xbfb8aa3b, v63
	v_mul_f32_e32 v134, 0xbfb8aa3b, v64
	v_mul_f32_e32 v135, 0xbfb8aa3b, v65
	v_mul_f32_e32 v136, 0xbfb8aa3b, v58
	v_mul_f32_e32 v137, 0xbfb8aa3b, v59
	v_mul_f32_e32 v138, 0xbfb8aa3b, v60
	v_mul_f32_e32 v139, 0xbfb8aa3b, v61
	v_exp_f32_e32 v132, v132
	v_exp_f32_e32 v133, v133
	v_exp_f32_e32 v134, v134
	v_exp_f32_e32 v135, v135
	v_exp_f32_e32 v136, v136
	v_exp_f32_e32 v137, v137
	v_exp_f32_e32 v138, v138
	v_exp_f32_e32 v139, v139
	v_add_f32_e32 v132, 1.0, v132
	v_add_f32_e32 v133, 1.0, v133
	v_add_f32_e32 v134, 1.0, v134
	v_add_f32_e32 v135, 1.0, v135
	v_add_f32_e32 v136, 1.0, v136
	v_add_f32_e32 v137, 1.0, v137
	v_add_f32_e32 v138, 1.0, v138
	v_add_f32_e32 v139, 1.0, v139
	v_rcp_f32_e32 v132, v132
	v_rcp_f32_e32 v133, v133
	v_rcp_f32_e32 v134, v134
	v_rcp_f32_e32 v135, v135
	v_rcp_f32_e32 v136, v136
; __device__ __forceinline__ unsigned cvt_pk_bf16(float lo, float hi) { unsigned r; asm volatile("v_cvt_pk_bf16_f32 %0, %1, %2" : "=v"(r) : "v"(lo), "v"(hi)); return r; }
; __device__ __forceinline__ float silu_f(float x) { return x * __builtin_amdgcn_rcpf(1.f + __expf(-x)); }
;     __device__ __forceinline__ void operator()(const f32x4 (&acc)[2][2][4][2], const pg8::Unit& u, int wr, int wc, int fr, int fq) const {
;     ...
;         } else {
;             const bool act = (sec == 3 || sec == 7);
;             const int col0 = 256 * half + 64 * wc + 8 * fq;
; #pragma unroll
;             for (int ai = 0; ai < 2; ++ai)
; #pragma unroll
;                 for (int m = 0; m < 4; ++m) {
;                     bf16_t* rowp = base + (size_t)(row0 + ai * 128 + m * 16) * 512 + col0;
; #pragma unroll
;                     for (int bj = 0; bj < 2; ++bj) { f32x4 v0 = acc[ai][bj][m][0], v1 = acc[ai][bj][m][1];
;                         if (act) { v0 = (f32x4){silu_f(v0[0]), silu_f(v0[1]), silu_f(v0[2]), silu_f(v0[3])}; v1 = (f32x4){silu_f(v1[0]), silu_f(v1[1]), silu_f(v1[2]), silu_f(v1[3])}; }
;                         u32x4 w; w.x = cvt_pk_bf16(v0[0], v0[1]); w.y = cvt_pk_bf16(v0[2], v0[3]); w.z = cvt_pk_bf16(v1[0], v1[1]); w.w = cvt_pk_bf16(v1[2], v1[3]);
;                         *(u32x4*)(rowp + 32 * bj) = w; }
;                 }
	v_rcp_f32_e32 v137, v137
	v_rcp_f32_e32 v138, v138
	v_rcp_f32_e32 v139, v139
	v_pk_mul_f32 v[132:133], v[62:63], v[132:133]
	v_pk_mul_f32 v[134:135], v[64:65], v[134:135]
	v_pk_mul_f32 v[136:137], v[58:59], v[136:137]
	v_pk_mul_f32 v[138:139], v[60:61], v[138:139]
	v_cvt_pk_bf16_f32 v200, v132, v133
	v_cvt_pk_bf16_f32 v201, v134, v135
	v_cvt_pk_bf16_f32 v202, v136, v137
	v_cvt_pk_bf16_f32 v203, v138, v139
	v_cndmask_b32_dpp v208, v204, v200, vcc quad_perm:[1,0,3,2] row_mask:0xf bank_mask:0xf
	v_cndmask_b32_dpp v209, v205, v201, vcc quad_perm:[1,0,3,2] row_mask:0xf bank_mask:0xf
	v_cndmask_b32_dpp v210, v206, v202, vcc quad_perm:[1,0,3,2] row_mask:0xf bank_mask:0xf
	v_cndmask_b32_dpp v211, v207, v203, vcc quad_perm:[1,0,3,2] row_mask:0xf bank_mask:0xf
	s_not_b64 vcc, vcc
	v_cndmask_b32_dpp v212, v200, v204, vcc quad_perm:[1,0,3,2] row_mask:0xf bank_mask:0xf
	v_cndmask_b32_dpp v213, v201, v205, vcc quad_perm:[1,0,3,2] row_mask:0xf bank_mask:0xf
	v_cndmask_b32_dpp v214, v202, v206, vcc quad_perm:[1,0,3,2] row_mask:0xf bank_mask:0xf
	v_cndmask_b32_dpp v215, v203, v207, vcc quad_perm:[1,0,3,2] row_mask:0xf bank_mask:0xf
	s_not_b64 vcc, vcc
	global_store_dwordx4 v[130:131], v[208:211], off nt
	global_store_dwordx4 v[130:131], v[212:215], off offset:1024 nt
	v_lshl_add_u64 v[130:131], v[130:131], 0, s[4:5]
	v_mul_f32_e32 v224, 0xbfb8aa3b, v38
	v_mul_f32_e32 v225, 0xbfb8aa3b, v39
	v_mul_f32_e32 v226, 0xbfb8aa3b, v40
	v_mul_f32_e32 v227, 0xbfb8aa3b, v41
	v_mul_f32_e32 v228, 0xbfb8aa3b, v34
	v_mul_f32_e32 v229, 0xbfb8aa3b, v35
	v_mul_f32_e32 v230, 0xbfb8aa3b, v36
	v_mul_f32_e32 v231, 0xbfb8aa3b, v37
	v_exp_f32_e32 v224, v224
	v_exp_f32_e32 v225, v225
	v_exp_f32_e32 v226, v226
	v_exp_f32_e32 v227, v227
	v_exp_f32_e32 v228, v228
	v_exp_f32_e32 v229, v229
	v_exp_f32_e32 v230, v230
	v_exp_f32_e32 v231, v231
	v_add_f32_e32 v224, 1.0, v224
	v_add_f32_e32 v225, 1.0, v225
	v_add_f32_e32 v226, 1.0, v226
	v_add_f32_e32 v227, 1.0, v227
	v_add_f32_e32 v228, 1.0, v228
	v_add_f32_e32 v229, 1.0, v229
	v_add_f32_e32 v230, 1.0, v230
	v_add_f32_e32 v231, 1.0, v231
	v_rcp_f32_e32 v224, v224
	v_rcp_f32_e32 v225, v225
	v_rcp_f32_e32 v226, v226
	v_rcp_f32_e32 v227, v227
	v_rcp_f32_e32 v228, v228
	v_rcp_f32_e32 v229, v229
	v_rcp_f32_e32 v230, v230
	v_rcp_f32_e32 v231, v231
	v_pk_mul_f32 v[224:225], v[38:39], v[224:225]
	v_pk_mul_f32 v[226:227], v[40:41], v[226:227]
	v_pk_mul_f32 v[228:229], v[34:35], v[228:229]
	v_pk_mul_f32 v[230:231], v[36:37], v[230:231]
	v_cvt_pk_bf16_f32 v204, v224, v225
	v_cvt_pk_bf16_f32 v205, v226, v227
	v_cvt_pk_bf16_f32 v206, v228, v229
	v_cvt_pk_bf16_f32 v207, v230, v231
	v_mul_f32_e32 v132, 0xbfb8aa3b, v46
	v_mul_f32_e32 v133, 0xbfb8aa3b, v47
	v_mul_f32_e32 v134, 0xbfb8aa3b, v48
	v_mul_f32_e32 v135, 0xbfb8aa3b, v49
	v_mul_f32_e32 v136, 0xbfb8aa3b, v42
	v_mul_f32_e32 v137, 0xbfb8aa3b, v43
	v_mul_f32_e32 v138, 0xbfb8aa3b, v44
	v_mul_f32_e32 v139, 0xbfb8aa3b, v45
	v_exp_f32_e32 v132, v132
	v_exp_f32_e32 v133, v133
	v_exp_f32_e32 v134, v134
	v_exp_f32_e32 v135, v135
	v_exp_f32_e32 v136, v136
	v_exp_f32_e32 v137, v137
	v_exp_f32_e32 v138, v138
	v_exp_f32_e32 v139, v139
	v_add_f32_e32 v132, 1.0, v132
	v_add_f32_e32 v133, 1.0, v133
	v_add_f32_e32 v134, 1.0, v134
	v_add_f32_e32 v135, 1.0, v135
	v_add_f32_e32 v136, 1.0, v136
	v_add_f32_e32 v137, 1.0, v137
	v_add_f32_e32 v138, 1.0, v138
	v_add_f32_e32 v139, 1.0, v139
	v_rcp_f32_e32 v132, v132
	v_rcp_f32_e32 v133, v133
	v_rcp_f32_e32 v134, v134
	v_rcp_f32_e32 v135, v135
	v_rcp_f32_e32 v136, v136
	v_rcp_f32_e32 v137, v137
	v_rcp_f32_e32 v138, v138
	v_rcp_f32_e32 v139, v139
	v_pk_mul_f32 v[132:133], v[46:47], v[132:133]
	v_pk_mul_f32 v[134:135], v[48:49], v[134:135]
	v_pk_mul_f32 v[136:137], v[42:43], v[136:137]
	v_pk_mul_f32 v[138:139], v[44:45], v[138:139]
	v_cvt_pk_bf16_f32 v200, v132, v133
	v_cvt_pk_bf16_f32 v201, v134, v135
	v_cvt_pk_bf16_f32 v202, v136, v137
	v_cvt_pk_bf16_f32 v203, v138, v139
	v_cndmask_b32_dpp v216, v204, v200, vcc quad_perm:[1,0,3,2] row_mask:0xf bank_mask:0xf
	v_cndmask_b32_dpp v217, v205, v201, vcc quad_perm:[1,0,3,2] row_mask:0xf bank_mask:0xf
	v_cndmask_b32_dpp v218, v206, v202, vcc quad_perm:[1,0,3,2] row_mask:0xf bank_mask:0xf
	v_cndmask_b32_dpp v219, v207, v203, vcc quad_perm:[1,0,3,2] row_mask:0xf bank_mask:0xf
	s_not_b64 vcc, vcc
	v_cndmask_b32_dpp v220, v200, v204, vcc quad_perm:[1,0,3,2] row_mask:0xf bank_mask:0xf
	v_cndmask_b32_dpp v221, v201, v205, vcc quad_perm:[1,0,3,2] row_mask:0xf bank_mask:0xf
	v_cndmask_b32_dpp v222, v202, v206, vcc quad_perm:[1,0,3,2] row_mask:0xf bank_mask:0xf
	v_cndmask_b32_dpp v223, v203, v207, vcc quad_perm:[1,0,3,2] row_mask:0xf bank_mask:0xf
	s_not_b64 vcc, vcc
	global_store_dwordx4 v[130:131], v[216:219], off nt
	global_store_dwordx4 v[130:131], v[220:223], off offset:1024 nt
	v_lshl_add_u64 v[130:131], v[130:131], 0, s[4:5]
	v_mul_f32_e32 v224, 0xbfb8aa3b, v22
	v_mul_f32_e32 v225, 0xbfb8aa3b, v23
	v_mul_f32_e32 v226, 0xbfb8aa3b, v24
	v_mul_f32_e32 v227, 0xbfb8aa3b, v25
	v_mul_f32_e32 v228, 0xbfb8aa3b, v18
	v_mul_f32_e32 v229, 0xbfb8aa3b, v19
	v_mul_f32_e32 v230, 0xbfb8aa3b, v20
	v_mul_f32_e32 v231, 0xbfb8aa3b, v21
	v_exp_f32_e32 v224, v224
	v_exp_f32_e32 v225, v225
	v_exp_f32_e32 v226, v226
	v_exp_f32_e32 v227, v227
	v_exp_f32_e32 v228, v228
	v_exp_f32_e32 v229, v229
	v_exp_f32_e32 v230, v230
	v_exp_f32_e32 v231, v231
	v_add_f32_e32 v224, 1.0, v224
	v_add_f32_e32 v225, 1.0, v225
	v_add_f32_e32 v226, 1.0, v226
	v_add_f32_e32 v227, 1.0, v227
	v_add_f32_e32 v228, 1.0, v228
	v_add_f32_e32 v229, 1.0, v229
	v_add_f32_e32 v230, 1.0, v230
	v_add_f32_e32 v231, 1.0, v231
	v_rcp_f32_e32 v224, v224
	v_rcp_f32_e32 v225, v225
	v_rcp_f32_e32 v226, v226
; __device__ __forceinline__ unsigned cvt_pk_bf16(float lo, float hi) { unsigned r; asm volatile("v_cvt_pk_bf16_f32 %0, %1, %2" : "=v"(r) : "v"(lo), "v"(hi)); return r; }
; __device__ __forceinline__ float silu_f(float x) { return x * __builtin_amdgcn_rcpf(1.f + __expf(-x)); }
;     __device__ __forceinline__ void operator()(const f32x4 (&acc)[2][2][4][2], const pg8::Unit& u, int wr, int wc, int fr, int fq) const {
;     ...
;         } else {
;             const bool act = (sec == 3 || sec == 7);
;             const int col0 = 256 * half + 64 * wc + 8 * fq;
; #pragma unroll
;             for (int ai = 0; ai < 2; ++ai)
; #pragma unroll
;                 for (int m = 0; m < 4; ++m) {
;                     bf16_t* rowp = base + (size_t)(row0 + ai * 128 + m * 16) * 512 + col0;
; #pragma unroll
;                     for (int bj = 0; bj < 2; ++bj) { f32x4 v0 = acc[ai][bj][m][0], v1 = acc[ai][bj][m][1];
;                         if (act) { v0 = (f32x4){silu_f(v0[0]), silu_f(v0[1]), silu_f(v0[2]), silu_f(v0[3])}; v1 = (f32x4){silu_f(v1[0]), silu_f(v1[1]), silu_f(v1[2]), silu_f(v1[3])}; }
;                         u32x4 w; w.x = cvt_pk_bf16(v0[0], v0[1]); w.y = cvt_pk_bf16(v0[2], v0[3]); w.z = cvt_pk_bf16(v1[0], v1[1]); w.w = cvt_pk_bf16(v1[2], v1[3]);
;                         *(u32x4*)(rowp + 32 * bj) = w; }
;                 }
	v_rcp_f32_e32 v227, v227
	v_rcp_f32_e32 v228, v228
	v_rcp_f32_e32 v229, v229
	v_rcp_f32_e32 v230, v230
	v_rcp_f32_e32 v231, v231
	v_pk_mul_f32 v[224:225], v[22:23], v[224:225]
	v_pk_mul_f32 v[226:227], v[24:25], v[226:227]
	v_pk_mul_f32 v[228:229], v[18:19], v[228:229]
	v_pk_mul_f32 v[230:231], v[20:21], v[230:231]
	v_cvt_pk_bf16_f32 v204, v224, v225
	v_cvt_pk_bf16_f32 v205, v226, v227
	v_cvt_pk_bf16_f32 v206, v228, v229
	v_cvt_pk_bf16_f32 v207, v230, v231
	v_mul_f32_e32 v132, 0xbfb8aa3b, v30
	v_mul_f32_e32 v133, 0xbfb8aa3b, v31
	v_mul_f32_e32 v134, 0xbfb8aa3b, v32
	v_mul_f32_e32 v135, 0xbfb8aa3b, v33
	v_mul_f32_e32 v136, 0xbfb8aa3b, v26
	v_mul_f32_e32 v137, 0xbfb8aa3b, v27
	v_mul_f32_e32 v138, 0xbfb8aa3b, v28
	v_mul_f32_e32 v139, 0xbfb8aa3b, v29
	v_exp_f32_e32 v132, v132
	v_exp_f32_e32 v133, v133
	v_exp_f32_e32 v134, v134
	v_exp_f32_e32 v135, v135
	v_exp_f32_e32 v136, v136
	v_exp_f32_e32 v137, v137
	v_exp_f32_e32 v138, v138
	v_exp_f32_e32 v139, v139
	v_add_f32_e32 v132, 1.0, v132
	v_add_f32_e32 v133, 1.0, v133
	v_add_f32_e32 v134, 1.0, v134
	v_add_f32_e32 v135, 1.0, v135
	v_add_f32_e32 v136, 1.0, v136
	v_add_f32_e32 v137, 1.0, v137
	v_add_f32_e32 v138, 1.0, v138
	v_add_f32_e32 v139, 1.0, v139
	v_rcp_f32_e32 v132, v132
	v_rcp_f32_e32 v133, v133
	v_rcp_f32_e32 v134, v134
	v_rcp_f32_e32 v135, v135
	v_rcp_f32_e32 v136, v136
	v_rcp_f32_e32 v137, v137
	v_rcp_f32_e32 v138, v138
	v_rcp_f32_e32 v139, v139
	v_pk_mul_f32 v[132:133], v[30:31], v[132:133]
	v_pk_mul_f32 v[134:135], v[32:33], v[134:135]
	v_pk_mul_f32 v[136:137], v[26:27], v[136:137]
	v_pk_mul_f32 v[138:139], v[28:29], v[138:139]
	v_cvt_pk_bf16_f32 v200, v132, v133
	v_cvt_pk_bf16_f32 v201, v134, v135
	v_cvt_pk_bf16_f32 v202, v136, v137
	v_cvt_pk_bf16_f32 v203, v138, v139
	v_cndmask_b32_dpp v208, v204, v200, vcc quad_perm:[1,0,3,2] row_mask:0xf bank_mask:0xf
	v_cndmask_b32_dpp v209, v205, v201, vcc quad_perm:[1,0,3,2] row_mask:0xf bank_mask:0xf
	v_cndmask_b32_dpp v210, v206, v202, vcc quad_perm:[1,0,3,2] row_mask:0xf bank_mask:0xf
	v_cndmask_b32_dpp v211, v207, v203, vcc quad_perm:[1,0,3,2] row_mask:0xf bank_mask:0xf
	s_not_b64 vcc, vcc
	v_cndmask_b32_dpp v212, v200, v204, vcc quad_perm:[1,0,3,2] row_mask:0xf bank_mask:0xf
	v_cndmask_b32_dpp v213, v201, v205, vcc quad_perm:[1,0,3,2] row_mask:0xf bank_mask:0xf
	v_cndmask_b32_dpp v214, v202, v206, vcc quad_perm:[1,0,3,2] row_mask:0xf bank_mask:0xf
	v_cndmask_b32_dpp v215, v203, v207, vcc quad_perm:[1,0,3,2] row_mask:0xf bank_mask:0xf
	s_not_b64 vcc, vcc
	global_store_dwordx4 v[130:131], v[208:211], off nt
	global_store_dwordx4 v[130:131], v[212:215], off offset:1024 nt
	v_lshl_add_u64 v[130:131], v[130:131], 0, s[4:5]
	v_mul_f32_e32 v224, 0xbfb8aa3b, v6
	v_mul_f32_e32 v225, 0xbfb8aa3b, v7
	v_mul_f32_e32 v226, 0xbfb8aa3b, v8
	v_mul_f32_e32 v227, 0xbfb8aa3b, v9
	v_mul_f32_e32 v228, 0xbfb8aa3b, v2
	v_mul_f32_e32 v229, 0xbfb8aa3b, v3
	v_mul_f32_e32 v230, 0xbfb8aa3b, v4
	v_mul_f32_e32 v231, 0xbfb8aa3b, v5
	v_exp_f32_e32 v224, v224
	v_exp_f32_e32 v225, v225
	v_exp_f32_e32 v226, v226
	v_exp_f32_e32 v227, v227
	v_exp_f32_e32 v228, v228
	v_exp_f32_e32 v229, v229
	v_exp_f32_e32 v230, v230
	v_exp_f32_e32 v231, v231
	v_add_f32_e32 v224, 1.0, v224
	v_add_f32_e32 v225, 1.0, v225
	v_add_f32_e32 v226, 1.0, v226
	v_add_f32_e32 v227, 1.0, v227
	v_add_f32_e32 v228, 1.0, v228
	v_add_f32_e32 v229, 1.0, v229
	v_add_f32_e32 v230, 1.0, v230
	v_add_f32_e32 v231, 1.0, v231
	v_rcp_f32_e32 v224, v224
	v_rcp_f32_e32 v225, v225
	v_rcp_f32_e32 v226, v226
	v_rcp_f32_e32 v227, v227
	v_rcp_f32_e32 v228, v228
	v_rcp_f32_e32 v229, v229
	v_rcp_f32_e32 v230, v230
	v_rcp_f32_e32 v231, v231
	v_pk_mul_f32 v[224:225], v[6:7], v[224:225]
	v_pk_mul_f32 v[226:227], v[8:9], v[226:227]
	v_pk_mul_f32 v[228:229], v[2:3], v[228:229]
	v_pk_mul_f32 v[230:231], v[4:5], v[230:231]
	v_cvt_pk_bf16_f32 v204, v224, v225
	v_cvt_pk_bf16_f32 v205, v226, v227
	v_cvt_pk_bf16_f32 v206, v228, v229
	v_cvt_pk_bf16_f32 v207, v230, v231
	v_mul_f32_e32 v132, 0xbfb8aa3b, v14
	v_mul_f32_e32 v133, 0xbfb8aa3b, v15
	v_mul_f32_e32 v134, 0xbfb8aa3b, v16
	v_mul_f32_e32 v135, 0xbfb8aa3b, v17
	v_mul_f32_e32 v136, 0xbfb8aa3b, v10
	v_mul_f32_e32 v137, 0xbfb8aa3b, v11
	v_mul_f32_e32 v138, 0xbfb8aa3b, v12
	v_mul_f32_e32 v139, 0xbfb8aa3b, v13
	v_exp_f32_e32 v132, v132
	v_exp_f32_e32 v133, v133
	v_exp_f32_e32 v134, v134
	v_exp_f32_e32 v135, v135
	v_exp_f32_e32 v136, v136
	v_exp_f32_e32 v137, v137
	v_exp_f32_e32 v138, v138
	v_exp_f32_e32 v139, v139
	v_add_f32_e32 v132, 1.0, v132
	v_add_f32_e32 v133, 1.0, v133
	v_add_f32_e32 v134, 1.0, v134
	v_add_f32_e32 v135, 1.0, v135
	v_add_f32_e32 v136, 1.0, v136
	v_add_f32_e32 v137, 1.0, v137
	v_add_f32_e32 v138, 1.0, v138
	v_add_f32_e32 v139, 1.0, v139
	v_rcp_f32_e32 v132, v132
	v_rcp_f32_e32 v133, v133
	v_rcp_f32_e32 v134, v134
	v_rcp_f32_e32 v135, v135
	v_rcp_f32_e32 v136, v136
	v_rcp_f32_e32 v137, v137
	v_rcp_f32_e32 v138, v138
	v_rcp_f32_e32 v139, v139
	v_pk_mul_f32 v[132:133], v[14:15], v[132:133]
	v_pk_mul_f32 v[134:135], v[16:17], v[134:135]
	v_pk_mul_f32 v[136:137], v[10:11], v[136:137]
	v_pk_mul_f32 v[138:139], v[12:13], v[138:139]
	v_cvt_pk_bf16_f32 v200, v132, v133
	v_cvt_pk_bf16_f32 v201, v134, v135
	v_cvt_pk_bf16_f32 v202, v136, v137
	v_cvt_pk_bf16_f32 v203, v138, v139
	v_cndmask_b32_dpp v216, v204, v200, vcc quad_perm:[1,0,3,2] row_mask:0xf bank_mask:0xf
	v_cndmask_b32_dpp v217, v205, v201, vcc quad_perm:[1,0,3,2] row_mask:0xf bank_mask:0xf
	v_cndmask_b32_dpp v218, v206, v202, vcc quad_perm:[1,0,3,2] row_mask:0xf bank_mask:0xf
	v_cndmask_b32_dpp v219, v207, v203, vcc quad_perm:[1,0,3,2] row_mask:0xf bank_mask:0xf
	s_not_b64 vcc, vcc
	v_cndmask_b32_dpp v220, v200, v204, vcc quad_perm:[1,0,3,2] row_mask:0xf bank_mask:0xf
	v_cndmask_b32_dpp v221, v201, v205, vcc quad_perm:[1,0,3,2] row_mask:0xf bank_mask:0xf
	v_cndmask_b32_dpp v222, v202, v206, vcc quad_perm:[1,0,3,2] row_mask:0xf bank_mask:0xf
	v_cndmask_b32_dpp v223, v203, v207, vcc quad_perm:[1,0,3,2] row_mask:0xf bank_mask:0xf
	s_not_b64 vcc, vcc
	global_store_dwordx4 v[130:131], v[216:219], off nt
	global_store_dwordx4 v[130:131], v[220:223], off offset:1024 nt
	s_branch .Lp1e_done
; __device__ __forceinline__ unsigned cvt_pk_bf16(float lo, float hi) { unsigned r; asm volatile("v_cvt_pk_bf16_f32 %0, %1, %2" : "=v"(r) : "v"(lo), "v"(hi)); return r; }
; __device__ __forceinline__ float silu_f(float x) { return x * __builtin_amdgcn_rcpf(1.f + __expf(-x)); }
;     __device__ __forceinline__ void operator()(const f32x4 (&acc)[2][2][4][2], const pg8::Unit& u, int wr, int wc, int fr, int fq) const {
;     ...
;         } else {
;             const bool act = (sec == 3 || sec == 7);
;             const int col0 = 256 * half + 64 * wc + 8 * fq;
; #pragma unroll
;             for (int ai = 0; ai < 2; ++ai)
; #pragma unroll
;                 for (int m = 0; m < 4; ++m) {
;                     bf16_t* rowp = base + (size_t)(row0 + ai * 128 + m * 16) * 512 + col0;
; #pragma unroll
;                     for (int bj = 0; bj < 2; ++bj) { f32x4 v0 = acc[ai][bj][m][0], v1 = acc[ai][bj][m][1];
;                         if (act) { v0 = (f32x4){silu_f(v0[0]), silu_f(v0[1]), silu_f(v0[2]), silu_f(v0[3])}; v1 = (f32x4){silu_f(v1[0]), silu_f(v1[1]), silu_f(v1[2]), silu_f(v1[3])}; }
;                         u32x4 w; w.x = cvt_pk_bf16(v0[0], v0[1]); w.y = cvt_pk_bf16(v0[2], v0[3]); w.z = cvt_pk_bf16(v1[0], v1[1]); w.w = cvt_pk_bf16(v1[2], v1[3]);
;                         *(u32x4*)(rowp + 32 * bj) = w; }
;                 }
.Lp1e_plain:
	v_cvt_pk_bf16_f32 v204, v118, v119
	v_cvt_pk_bf16_f32 v205, v120, v121
	v_cvt_pk_bf16_f32 v206, v114, v115
	v_cvt_pk_bf16_f32 v207, v116, v117
	v_cvt_pk_bf16_f32 v200, v126, v127
	v_cvt_pk_bf16_f32 v201, v128, v129
	v_cvt_pk_bf16_f32 v202, v122, v123
	v_cvt_pk_bf16_f32 v203, v124, v125
	v_cndmask_b32_dpp v208, v204, v200, vcc quad_perm:[1,0,3,2] row_mask:0xf bank_mask:0xf
	v_cndmask_b32_dpp v209, v205, v201, vcc quad_perm:[1,0,3,2] row_mask:0xf bank_mask:0xf
	v_cndmask_b32_dpp v210, v206, v202, vcc quad_perm:[1,0,3,2] row_mask:0xf bank_mask:0xf
	v_cndmask_b32_dpp v211, v207, v203, vcc quad_perm:[1,0,3,2] row_mask:0xf bank_mask:0xf
	s_not_b64 vcc, vcc
	v_cndmask_b32_dpp v212, v200, v204, vcc quad_perm:[1,0,3,2] row_mask:0xf bank_mask:0xf
	v_cndmask_b32_dpp v213, v201, v205, vcc quad_perm:[1,0,3,2] row_mask:0xf bank_mask:0xf
	v_cndmask_b32_dpp v214, v202, v206, vcc quad_perm:[1,0,3,2] row_mask:0xf bank_mask:0xf
	v_cndmask_b32_dpp v215, v203, v207, vcc quad_perm:[1,0,3,2] row_mask:0xf bank_mask:0xf
	s_not_b64 vcc, vcc
	global_store_dwordx4 v[130:131], v[208:211], off nt
	global_store_dwordx4 v[130:131], v[212:215], off offset:1024 nt
	v_lshl_add_u64 v[130:131], v[130:131], 0, s[4:5]
	v_cvt_pk_bf16_f32 v204, v102, v103
	v_cvt_pk_bf16_f32 v205, v104, v105
	v_cvt_pk_bf16_f32 v206, v98, v99
	v_cvt_pk_bf16_f32 v207, v100, v101
	v_cvt_pk_bf16_f32 v200, v110, v111
	v_cvt_pk_bf16_f32 v201, v112, v113
	v_cvt_pk_bf16_f32 v202, v106, v107
	v_cvt_pk_bf16_f32 v203, v108, v109
	v_cndmask_b32_dpp v216, v204, v200, vcc quad_perm:[1,0,3,2] row_mask:0xf bank_mask:0xf
	v_cndmask_b32_dpp v217, v205, v201, vcc quad_perm:[1,0,3,2] row_mask:0xf bank_mask:0xf
	v_cndmask_b32_dpp v218, v206, v202, vcc quad_perm:[1,0,3,2] row_mask:0xf bank_mask:0xf
	v_cndmask_b32_dpp v219, v207, v203, vcc quad_perm:[1,0,3,2] row_mask:0xf bank_mask:0xf
	s_not_b64 vcc, vcc
	v_cndmask_b32_dpp v220, v200, v204, vcc quad_perm:[1,0,3,2] row_mask:0xf bank_mask:0xf
	v_cndmask_b32_dpp v221, v201, v205, vcc quad_perm:[1,0,3,2] row_mask:0xf bank_mask:0xf
	v_cndmask_b32_dpp v222, v202, v206, vcc quad_perm:[1,0,3,2] row_mask:0xf bank_mask:0xf
	v_cndmask_b32_dpp v223, v203, v207, vcc quad_perm:[1,0,3,2] row_mask:0xf bank_mask:0xf
	s_not_b64 vcc, vcc
	global_store_dwordx4 v[130:131], v[216:219], off nt
	global_store_dwordx4 v[130:131], v[220:223], off offset:1024 nt
	v_lshl_add_u64 v[130:131], v[130:131], 0, s[4:5]
	v_cvt_pk_bf16_f32 v204, v86, v87
	v_cvt_pk_bf16_f32 v205, v88, v89
	v_cvt_pk_bf16_f32 v206, v82, v83
	v_cvt_pk_bf16_f32 v207, v84, v85
	v_cvt_pk_bf16_f32 v200, v94, v95
	v_cvt_pk_bf16_f32 v201, v96, v97
	v_cvt_pk_bf16_f32 v202, v90, v91
	v_cvt_pk_bf16_f32 v203, v92, v93
	v_cndmask_b32_dpp v208, v204, v200, vcc quad_perm:[1,0,3,2] row_mask:0xf bank_mask:0xf
	v_cndmask_b32_dpp v209, v205, v201, vcc quad_perm:[1,0,3,2] row_mask:0xf bank_mask:0xf
	v_cndmask_b32_dpp v210, v206, v202, vcc quad_perm:[1,0,3,2] row_mask:0xf bank_mask:0xf
	v_cndmask_b32_dpp v211, v207, v203, vcc quad_perm:[1,0,3,2] row_mask:0xf bank_mask:0xf
	s_not_b64 vcc, vcc
	v_cndmask_b32_dpp v212, v200, v204, vcc quad_perm:[1,0,3,2] row_mask:0xf bank_mask:0xf
	v_cndmask_b32_dpp v213, v201, v205, vcc quad_perm:[1,0,3,2] row_mask:0xf bank_mask:0xf
	v_cndmask_b32_dpp v214, v202, v206, vcc quad_perm:[1,0,3,2] row_mask:0xf bank_mask:0xf
	v_cndmask_b32_dpp v215, v203, v207, vcc quad_perm:[1,0,3,2] row_mask:0xf bank_mask:0xf
	s_not_b64 vcc, vcc
	global_store_dwordx4 v[130:131], v[208:211], off nt
	global_store_dwordx4 v[130:131], v[212:215], off offset:1024 nt
	v_lshl_add_u64 v[130:131], v[130:131], 0, s[4:5]
	v_cvt_pk_bf16_f32 v204, v70, v71
	v_cvt_pk_bf16_f32 v205, v72, v73
	v_cvt_pk_bf16_f32 v206, v66, v67
	v_cvt_pk_bf16_f32 v207, v68, v69
	v_cvt_pk_bf16_f32 v200, v78, v79
	v_cvt_pk_bf16_f32 v201, v80, v81
	v_cvt_pk_bf16_f32 v202, v74, v75
	v_cvt_pk_bf16_f32 v203, v76, v77
	v_cndmask_b32_dpp v216, v204, v200, vcc quad_perm:[1,0,3,2] row_mask:0xf bank_mask:0xf
	v_cndmask_b32_dpp v217, v205, v201, vcc quad_perm:[1,0,3,2] row_mask:0xf bank_mask:0xf
	v_cndmask_b32_dpp v218, v206, v202, vcc quad_perm:[1,0,3,2] row_mask:0xf bank_mask:0xf
	v_cndmask_b32_dpp v219, v207, v203, vcc quad_perm:[1,0,3,2] row_mask:0xf bank_mask:0xf
	s_not_b64 vcc, vcc
	v_cndmask_b32_dpp v220, v200, v204, vcc quad_perm:[1,0,3,2] row_mask:0xf bank_mask:0xf
	v_cndmask_b32_dpp v221, v201, v205, vcc quad_perm:[1,0,3,2] row_mask:0xf bank_mask:0xf
	v_cndmask_b32_dpp v222, v202, v206, vcc quad_perm:[1,0,3,2] row_mask:0xf bank_mask:0xf
	v_cndmask_b32_dpp v223, v203, v207, vcc quad_perm:[1,0,3,2] row_mask:0xf bank_mask:0xf
	s_not_b64 vcc, vcc
	global_store_dwordx4 v[130:131], v[216:219], off nt
	global_store_dwordx4 v[130:131], v[220:223], off offset:1024 nt
	s_mov_b64 s[4:5], 0x14000
; __device__ __forceinline__ unsigned cvt_pk_bf16(float lo, float hi) { unsigned r; asm volatile("v_cvt_pk_bf16_f32 %0, %1, %2" : "=v"(r) : "v"(lo), "v"(hi)); return r; }
; __device__ __forceinline__ float silu_f(float x) { return x * __builtin_amdgcn_rcpf(1.f + __expf(-x)); }
;     __device__ __forceinline__ void operator()(const f32x4 (&acc)[2][2][4][2], const pg8::Unit& u, int wr, int wc, int fr, int fq) const {
;     ...
;         } else {
;             const bool act = (sec == 3 || sec == 7);
;             const int col0 = 256 * half + 64 * wc + 8 * fq;
; #pragma unroll
;             for (int ai = 0; ai < 2; ++ai)
; #pragma unroll
;                 for (int m = 0; m < 4; ++m) {
;                     bf16_t* rowp = base + (size_t)(row0 + ai * 128 + m * 16) * 512 + col0;
; #pragma unroll
;                     for (int bj = 0; bj < 2; ++bj) { f32x4 v0 = acc[ai][bj][m][0], v1 = acc[ai][bj][m][1];
;                         if (act) { v0 = (f32x4){silu_f(v0[0]), silu_f(v0[1]), silu_f(v0[2]), silu_f(v0[3])}; v1 = (f32x4){silu_f(v1[0]), silu_f(v1[1]), silu_f(v1[2]), silu_f(v1[3])}; }
;                         u32x4 w; w.x = cvt_pk_bf16(v0[0], v0[1]); w.y = cvt_pk_bf16(v0[2], v0[3]); w.z = cvt_pk_bf16(v1[0], v1[1]); w.w = cvt_pk_bf16(v1[2], v1[3]);
;                         *(u32x4*)(rowp + 32 * bj) = w; }
;                 }
	v_lshl_add_u64 v[130:131], v[130:131], 0, s[4:5]
	s_mov_b64 s[4:5], 0x4000
	v_cvt_pk_bf16_f32 v204, v54, v55
	v_cvt_pk_bf16_f32 v205, v56, v57
	v_cvt_pk_bf16_f32 v206, v50, v51
	v_cvt_pk_bf16_f32 v207, v52, v53
	v_cvt_pk_bf16_f32 v200, v62, v63
	v_cvt_pk_bf16_f32 v201, v64, v65
	v_cvt_pk_bf16_f32 v202, v58, v59
	v_cvt_pk_bf16_f32 v203, v60, v61
	v_cndmask_b32_dpp v208, v204, v200, vcc quad_perm:[1,0,3,2] row_mask:0xf bank_mask:0xf
	v_cndmask_b32_dpp v209, v205, v201, vcc quad_perm:[1,0,3,2] row_mask:0xf bank_mask:0xf
	v_cndmask_b32_dpp v210, v206, v202, vcc quad_perm:[1,0,3,2] row_mask:0xf bank_mask:0xf
	v_cndmask_b32_dpp v211, v207, v203, vcc quad_perm:[1,0,3,2] row_mask:0xf bank_mask:0xf
	s_not_b64 vcc, vcc
	v_cndmask_b32_dpp v212, v200, v204, vcc quad_perm:[1,0,3,2] row_mask:0xf bank_mask:0xf
	v_cndmask_b32_dpp v213, v201, v205, vcc quad_perm:[1,0,3,2] row_mask:0xf bank_mask:0xf
	v_cndmask_b32_dpp v214, v202, v206, vcc quad_perm:[1,0,3,2] row_mask:0xf bank_mask:0xf
	v_cndmask_b32_dpp v215, v203, v207, vcc quad_perm:[1,0,3,2] row_mask:0xf bank_mask:0xf
	s_not_b64 vcc, vcc
	global_store_dwordx4 v[130:131], v[208:211], off nt
	global_store_dwordx4 v[130:131], v[212:215], off offset:1024 nt
	v_lshl_add_u64 v[130:131], v[130:131], 0, s[4:5]
	v_cvt_pk_bf16_f32 v204, v38, v39
	v_cvt_pk_bf16_f32 v205, v40, v41
	v_cvt_pk_bf16_f32 v206, v34, v35
	v_cvt_pk_bf16_f32 v207, v36, v37
	v_cvt_pk_bf16_f32 v200, v46, v47
	v_cvt_pk_bf16_f32 v201, v48, v49
	v_cvt_pk_bf16_f32 v202, v42, v43
	v_cvt_pk_bf16_f32 v203, v44, v45
	v_cndmask_b32_dpp v216, v204, v200, vcc quad_perm:[1,0,3,2] row_mask:0xf bank_mask:0xf
	v_cndmask_b32_dpp v217, v205, v201, vcc quad_perm:[1,0,3,2] row_mask:0xf bank_mask:0xf
	v_cndmask_b32_dpp v218, v206, v202, vcc quad_perm:[1,0,3,2] row_mask:0xf bank_mask:0xf
	v_cndmask_b32_dpp v219, v207, v203, vcc quad_perm:[1,0,3,2] row_mask:0xf bank_mask:0xf
	s_not_b64 vcc, vcc
	v_cndmask_b32_dpp v220, v200, v204, vcc quad_perm:[1,0,3,2] row_mask:0xf bank_mask:0xf
	v_cndmask_b32_dpp v221, v201, v205, vcc quad_perm:[1,0,3,2] row_mask:0xf bank_mask:0xf
	v_cndmask_b32_dpp v222, v202, v206, vcc quad_perm:[1,0,3,2] row_mask:0xf bank_mask:0xf
	v_cndmask_b32_dpp v223, v203, v207, vcc quad_perm:[1,0,3,2] row_mask:0xf bank_mask:0xf
	s_not_b64 vcc, vcc
	global_store_dwordx4 v[130:131], v[216:219], off nt
	global_store_dwordx4 v[130:131], v[220:223], off offset:1024 nt
	v_lshl_add_u64 v[130:131], v[130:131], 0, s[4:5]
	v_cvt_pk_bf16_f32 v204, v22, v23
	v_cvt_pk_bf16_f32 v205, v24, v25
	v_cvt_pk_bf16_f32 v206, v18, v19
	v_cvt_pk_bf16_f32 v207, v20, v21
	v_cvt_pk_bf16_f32 v200, v30, v31
	v_cvt_pk_bf16_f32 v201, v32, v33
	v_cvt_pk_bf16_f32 v202, v26, v27
	v_cvt_pk_bf16_f32 v203, v28, v29
	v_cndmask_b32_dpp v208, v204, v200, vcc quad_perm:[1,0,3,2] row_mask:0xf bank_mask:0xf
	v_cndmask_b32_dpp v209, v205, v201, vcc quad_perm:[1,0,3,2] row_mask:0xf bank_mask:0xf
	v_cndmask_b32_dpp v210, v206, v202, vcc quad_perm:[1,0,3,2] row_mask:0xf bank_mask:0xf
	v_cndmask_b32_dpp v211, v207, v203, vcc quad_perm:[1,0,3,2] row_mask:0xf bank_mask:0xf
	s_not_b64 vcc, vcc
	v_cndmask_b32_dpp v212, v200, v204, vcc quad_perm:[1,0,3,2] row_mask:0xf bank_mask:0xf
	v_cndmask_b32_dpp v213, v201, v205, vcc quad_perm:[1,0,3,2] row_mask:0xf bank_mask:0xf
	v_cndmask_b32_dpp v214, v202, v206, vcc quad_perm:[1,0,3,2] row_mask:0xf bank_mask:0xf
	v_cndmask_b32_dpp v215, v203, v207, vcc quad_perm:[1,0,3,2] row_mask:0xf bank_mask:0xf
	s_not_b64 vcc, vcc
	global_store_dwordx4 v[130:131], v[208:211], off nt
	global_store_dwordx4 v[130:131], v[212:215], off offset:1024 nt
	v_lshl_add_u64 v[130:131], v[130:131], 0, s[4:5]
	v_cvt_pk_bf16_f32 v204, v6, v7
	v_cvt_pk_bf16_f32 v205, v8, v9
	v_cvt_pk_bf16_f32 v206, v2, v3
	v_cvt_pk_bf16_f32 v207, v4, v5
	v_cvt_pk_bf16_f32 v200, v14, v15
	v_cvt_pk_bf16_f32 v201, v16, v17
	v_cvt_pk_bf16_f32 v202, v10, v11
	v_cvt_pk_bf16_f32 v203, v12, v13
	v_cndmask_b32_dpp v216, v204, v200, vcc quad_perm:[1,0,3,2] row_mask:0xf bank_mask:0xf
	v_cndmask_b32_dpp v217, v205, v201, vcc quad_perm:[1,0,3,2] row_mask:0xf bank_mask:0xf
	v_cndmask_b32_dpp v218, v206, v202, vcc quad_perm:[1,0,3,2] row_mask:0xf bank_mask:0xf
	v_cndmask_b32_dpp v219, v207, v203, vcc quad_perm:[1,0,3,2] row_mask:0xf bank_mask:0xf
	s_not_b64 vcc, vcc
	v_cndmask_b32_dpp v220, v200, v204, vcc quad_perm:[1,0,3,2] row_mask:0xf bank_mask:0xf
	v_cndmask_b32_dpp v221, v201, v205, vcc quad_perm:[1,0,3,2] row_mask:0xf bank_mask:0xf
	v_cndmask_b32_dpp v222, v202, v206, vcc quad_perm:[1,0,3,2] row_mask:0xf bank_mask:0xf
	v_cndmask_b32_dpp v223, v203, v207, vcc quad_perm:[1,0,3,2] row_mask:0xf bank_mask:0xf
	s_not_b64 vcc, vcc
	global_store_dwordx4 v[130:131], v[216:219], off nt
	global_store_dwordx4 v[130:131], v[220:223], off offset:1024 nt

; __device__ __forceinline__ unsigned cvt_pk_bf16(float lo, float hi) { unsigned r; asm volatile("v_cvt_pk_bf16_f32 %0, %1, %2" : "=v"(r) : "v"(lo), "v"(hi)); return r; }
;     __device__ __forceinline__ void operator()(const f32x4 (&acc)[2][2][4][2], const pg8::Unit& u, int wr, int wc, int fr, int fq) const {
;     ...
;         } else if (sec == 4 || sec == 5) {
;             const float osc = sec == 5 ? 0.08838834764831845f : 1.f;
;             const int col0 = 256 * half + 128 * (wc >> 1) + 32 * (wc & 1) + 8 * fq, i0 = 32 * (wc & 1) + 8 * fq;
;             const int tb = row0 < NP ? (row0 & 4095) : row0 - NP;
;             f32x4 c[2], sn[2], c16[2], s16[2];
; #pragma unroll
;             for (int e = 0; e < 2; ++e) { c[e] = *(const f32x4*)(ropec + tb * 64 + i0 + 4 * e); sn[e] = *(const f32x4*)(ropes + tb * 64 + i0 + 4 * e);
;                 c16[e] = *(const f32x4*)(ropec + 16 * 64 + i0 + 4 * e); s16[e] = *(const f32x4*)(ropes + 16 * 64 + i0 + 4 * e); }
;             asm volatile("" ::: "memory");
; #pragma unroll
;             for (int k = 0; k < 12; ++k) {
;                 if (k < 4 || k >= 8) {
;                     const int ai = k >> 3, m = k & 3;
;                     const int row = row0 + ai * 128 + m * 16;
;                     const f32x4 c0 = c[0] * osc, c1 = c[1] * osc, s0 = sn[0] * osc, s1 = sn[1] * osc;
;                     const f32x4 a0 = acc[ai][0][m][0], a1 = acc[ai][0][m][1], b0 = acc[ai][1][m][0], b1 = acc[ai][1][m][1];
;                     const f32x4 o10 = a0 * c0 - b0 * s0, o11 = a1 * c1 - b1 * s1, o20 = a0 * s0 + b0 * c0, o21 = a1 * s1 + b1 * c1;
;                     bf16_t* rowp = base + (size_t)row * 512 + col0;
;                     u32x4 w; w.x = cvt_pk_bf16(o10[0], o10[1]); w.y = cvt_pk_bf16(o10[2], o10[3]); w.z = cvt_pk_bf16(o11[0], o11[1]); w.w = cvt_pk_bf16(o11[2], o11[3]);
;                     *(u32x4*)(rowp) = w;
;                     w.x = cvt_pk_bf16(o20[0], o20[1]); w.y = cvt_pk_bf16(o20[2], o20[3]); w.z = cvt_pk_bf16(o21[0], o21[1]); w.w = cvt_pk_bf16(o21[2], o21[3]);
;                     *(u32x4*)(rowp + 64) = w;
.LBB0_202:
	s_and_b64 vcc, exec, s[4:5]
	s_cbranch_vccz .LBB0_204
	v_and_b32_e32 v130, 0xfcf, v172
	v_add_u32_e32 v131, 0xffff0000, v172
	v_cmp_gt_i32_e32 vcc, s77, v172
	s_cmp_eq_u32 s41, 5
	v_lshl_or_b32 v154, s27, 9, v186
	v_cndmask_b32_e32 v130, v131, v130, vcc
	v_lshlrev_b32_e32 v130, 6, v130
	v_ashrrev_i32_e32 v131, 31, v130
	v_lshlrev_b64 v[130:131], 2, v[130:131]
	v_lshl_add_u64 v[132:133], v[156:157], 0, v[130:131]
	global_load_dwordx4 v[192:195], v[132:133], off
	global_load_dwordx4 v[196:199], v[132:133], off offset:16
	v_lshl_add_u64 v[130:131], v[158:159], 0, v[130:131]
	global_load_dwordx4 v[200:203], v[130:131], off
	global_load_dwordx4 v[204:207], v[130:131], off offset:16
	global_load_dwordx4 v[142:145], v[162:163], off
	global_load_dwordx4 v[134:137], v[162:163], off offset:16
	global_load_dwordx4 v[138:141], v[160:161], off
	s_nop 0
	global_load_dwordx4 v[130:133], v[160:161], off offset:16
	s_cselect_b64 vcc, -1, 0
	v_cndmask_b32_e32 v176, 1.0, v189, vcc
	v_ashrrev_i32_e32 v173, 31, v172
	v_lshl_add_u64 v[178:179], s[48:49], 0, v[154:155]
	v_lshlrev_b64 v[174:175], 10, v[172:173]
	v_lshl_add_u64 v[174:175], v[178:179], 0, v[174:175]
	v_or_b32_e32 v208, 16, v172
	v_ashrrev_i32_e32 v209, 31, v208
	s_waitcnt vmcnt(0)
	v_pk_mul_f32 v[220:221], v[176:177], v[200:201] op_sel_hi:[0,1]
	v_pk_mul_f32 v[218:219], v[176:177], v[202:203] op_sel_hi:[0,1]
	v_pk_mul_f32 v[212:213], v[176:177], v[192:193] op_sel_hi:[0,1]
	v_pk_mul_f32 v[228:229], v[200:201], v[142:143]
	v_pk_mul_f32 v[244:245], v[118:119], v[220:221]
	v_pk_mul_f32 v[210:211], v[176:177], v[194:195] op_sel_hi:[0,1]
	v_pk_mul_f32 v[222:223], v[176:177], v[206:207] op_sel_hi:[0,1]
	v_pk_mul_f32 v[224:225], v[176:177], v[204:205] op_sel_hi:[0,1]
	v_pk_mul_f32 v[226:227], v[202:203], v[144:145]
	v_pk_mul_f32 v[230:231], v[194:195], v[144:145]
	v_pk_mul_f32 v[232:233], v[192:193], v[142:143]
	v_pk_mul_f32 v[242:243], v[120:121], v[218:219]
	v_pk_fma_f32 v[228:229], v[192:193], v[138:139], v[228:229] neg_lo:[0,0,1] neg_hi:[0,0,1]
	v_pk_fma_f32 v[192:193], v[126:127], v[212:213], v[244:245] neg_lo:[0,0,1] neg_hi:[0,0,1]
	v_pk_mul_f32 v[214:215], v[176:177], v[198:199] op_sel_hi:[0,1]
	v_pk_mul_f32 v[216:217], v[176:177], v[196:197] op_sel_hi:[0,1]
	v_pk_mul_f32 v[234:235], v[206:207], v[136:137]
	v_pk_mul_f32 v[238:239], v[198:199], v[136:137]
	v_pk_mul_f32 v[240:241], v[196:197], v[134:135]
	v_pk_mul_f32 v[246:247], v[116:117], v[222:223]
	v_pk_mul_f32 v[248:249], v[114:115], v[224:225]
	v_pk_mul_f32 v[218:219], v[128:129], v[218:219]
	v_pk_mul_f32 v[220:221], v[126:127], v[220:221]
	v_pk_fma_f32 v[226:227], v[194:195], v[140:141], v[226:227] neg_lo:[0,0,1] neg_hi:[0,0,1]
	v_pk_fma_f32 v[202:203], v[202:203], v[140:141], v[230:231]
	v_pk_fma_f32 v[194:195], v[128:129], v[210:211], v[242:243] neg_lo:[0,0,1] neg_hi:[0,0,1]
	v_cvt_pk_bf16_f32 v192, v192, v193
	v_pk_mul_f32 v[236:237], v[204:205], v[134:135]
	v_cvt_pk_bf16_f32 v193, v194, v195
	v_pk_mul_f32 v[222:223], v[124:125], v[222:223]
	v_pk_mul_f32 v[224:225], v[122:123], v[224:225]
	v_pk_fma_f32 v[200:201], v[200:201], v[138:139], v[232:233]
	v_pk_fma_f32 v[198:199], v[198:199], v[132:133], v[234:235] neg_lo:[0,0,1] neg_hi:[0,0,1]
	v_pk_fma_f32 v[206:207], v[206:207], v[132:133], v[238:239]
	v_pk_fma_f32 v[204:205], v[204:205], v[130:131], v[240:241]
	v_pk_fma_f32 v[230:231], v[124:125], v[214:215], v[246:247] neg_lo:[0,0,1] neg_hi:[0,0,1]
	v_pk_fma_f32 v[232:233], v[122:123], v[216:217], v[248:249] neg_lo:[0,0,1] neg_hi:[0,0,1]
	v_pk_fma_f32 v[210:211], v[120:121], v[210:211], v[218:219]
	v_pk_fma_f32 v[212:213], v[118:119], v[212:213], v[220:221]
	v_pk_mul_f32 v[218:219], v[176:177], v[226:227] op_sel_hi:[0,1]
	v_pk_mul_f32 v[234:235], v[176:177], v[202:203] op_sel_hi:[0,1]
	v_cvt_pk_bf16_f32 v194, v232, v233
	v_cvt_pk_bf16_f32 v195, v230, v231
	global_store_dwordx4 v[174:175], v[192:195], off nt
	v_pk_fma_f32 v[196:197], v[196:197], v[130:131], v[236:237] neg_lo:[0,0,1] neg_hi:[0,0,1]
	v_pk_fma_f32 v[214:215], v[116:117], v[214:215], v[222:223]
	v_cvt_pk_bf16_f32 v192, v212, v213
	v_cvt_pk_bf16_f32 v193, v210, v211
	v_pk_fma_f32 v[216:217], v[114:115], v[216:217], v[224:225]
	v_pk_mul_f32 v[222:223], v[176:177], v[198:199] op_sel_hi:[0,1]
	v_pk_mul_f32 v[238:239], v[176:177], v[206:207] op_sel_hi:[0,1]
	v_pk_mul_f32 v[240:241], v[176:177], v[204:205] op_sel_hi:[0,1]
	v_pk_mul_f32 v[230:231], v[104:105], v[234:235]
	v_cvt_pk_bf16_f32 v194, v216, v217
	v_cvt_pk_bf16_f32 v195, v214, v215
	global_store_dwordx4 v[174:175], v[192:195], off offset:128 nt
	v_pk_mul_f32 v[224:225], v[176:177], v[196:197] op_sel_hi:[0,1]
	v_pk_mul_f32 v[236:237], v[176:177], v[200:201] op_sel_hi:[0,1]
	v_pk_mul_f32 v[192:193], v[104:105], v[218:219]
	v_pk_mul_f32 v[242:243], v[100:101], v[238:239]
	v_pk_mul_f32 v[244:245], v[98:99], v[240:241]
	v_pk_fma_f32 v[210:211], v[112:113], v[218:219], v[230:231] neg_lo:[0,0,1] neg_hi:[0,0,1]
	v_pk_fma_f32 v[218:219], v[112:113], v[234:235], v[192:193]
	v_pk_mul_f32 v[192:193], v[100:101], v[222:223]
	v_pk_mul_f32 v[220:221], v[176:177], v[228:229] op_sel_hi:[0,1]
	v_pk_mul_f32 v[232:233], v[102:103], v[236:237]
	v_pk_fma_f32 v[214:215], v[108:109], v[222:223], v[242:243] neg_lo:[0,0,1] neg_hi:[0,0,1]
	v_pk_fma_f32 v[194:195], v[106:107], v[224:225], v[244:245] neg_lo:[0,0,1] neg_hi:[0,0,1]
	v_pk_fma_f32 v[222:223], v[108:109], v[238:239], v[192:193]
	v_lshlrev_b64 v[192:193], 10, v[208:209]
	v_pk_fma_f32 v[212:213], v[110:111], v[220:221], v[232:233] neg_lo:[0,0,1] neg_hi:[0,0,1]
	v_pk_mul_f32 v[216:217], v[102:103], v[220:221]
	v_pk_mul_f32 v[220:221], v[98:99], v[224:225]
; __device__ __forceinline__ unsigned cvt_pk_bf16(float lo, float hi) { unsigned r; asm volatile("v_cvt_pk_bf16_f32 %0, %1, %2" : "=v"(r) : "v"(lo), "v"(hi)); return r; }
;     __device__ __forceinline__ void operator()(const f32x4 (&acc)[2][2][4][2], const pg8::Unit& u, int wr, int wc, int fr, int fq) const {
;     ...
;             for (int k = 0; k < 12; ++k) {
;                 if (k < 4 || k >= 8) {
;                     const int ai = k >> 3, m = k & 3;
;                     const int row = row0 + ai * 128 + m * 16;
;                     const f32x4 c0 = c[0] * osc, c1 = c[1] * osc, s0 = sn[0] * osc, s1 = sn[1] * osc;
;                     const f32x4 a0 = acc[ai][0][m][0], a1 = acc[ai][0][m][1], b0 = acc[ai][1][m][0], b1 = acc[ai][1][m][1];
;                     const f32x4 o10 = a0 * c0 - b0 * s0, o11 = a1 * c1 - b1 * s1, o20 = a0 * s0 + b0 * c0, o21 = a1 * s1 + b1 * c1;
;                     bf16_t* rowp = base + (size_t)row * 512 + col0;
;                     u32x4 w; w.x = cvt_pk_bf16(o10[0], o10[1]); w.y = cvt_pk_bf16(o10[2], o10[3]); w.z = cvt_pk_bf16(o11[0], o11[1]); w.w = cvt_pk_bf16(o11[2], o11[3]);
;                     *(u32x4*)(rowp) = w;
;                     w.x = cvt_pk_bf16(o20[0], o20[1]); w.y = cvt_pk_bf16(o20[2], o20[3]); w.z = cvt_pk_bf16(o21[0], o21[1]); w.w = cvt_pk_bf16(o21[2], o21[3]);
;                     *(u32x4*)(rowp + 64) = w;
;                 }
;                 if (k < 11) {
; #pragma unroll
;                     for (int e = 0; e < 2; ++e) { const f32x4 cn = c[e] * c16[e] - sn[e] * s16[e]; sn[e] = sn[e] * c16[e] + c[e] * s16[e]; c[e] = cn; } }
	v_lshl_add_u64 v[208:209], v[178:179], 0, v[192:193]
	v_cvt_pk_bf16_f32 v192, v212, v213
	v_cvt_pk_bf16_f32 v193, v210, v211
	v_cvt_pk_bf16_f32 v194, v194, v195
	v_cvt_pk_bf16_f32 v195, v214, v215
	v_pk_fma_f32 v[216:217], v[110:111], v[236:237], v[216:217]
	v_pk_fma_f32 v[220:221], v[106:107], v[240:241], v[220:221]
	global_store_dwordx4 v[208:209], v[192:195], off nt
	s_nop 1
	v_cvt_pk_bf16_f32 v192, v216, v217
	v_cvt_pk_bf16_f32 v193, v218, v219
	v_cvt_pk_bf16_f32 v194, v220, v221
	v_cvt_pk_bf16_f32 v195, v222, v223
	global_store_dwordx4 v[208:209], v[192:195], off offset:128 nt
	s_nop 1
	v_pk_mul_f32 v[192:193], v[144:145], v[202:203]
	v_pk_mul_f32 v[194:195], v[142:143], v[200:201]
	v_pk_fma_f32 v[208:209], v[140:141], v[226:227], v[192:193] neg_lo:[0,0,1] neg_hi:[0,0,1]
	v_pk_fma_f32 v[210:211], v[138:139], v[228:229], v[194:195] neg_lo:[0,0,1] neg_hi:[0,0,1]
	v_pk_mul_f32 v[192:193], v[144:145], v[226:227]
	v_pk_mul_f32 v[194:195], v[142:143], v[228:229]
	v_pk_fma_f32 v[202:203], v[140:141], v[202:203], v[192:193]
	v_pk_fma_f32 v[200:201], v[138:139], v[200:201], v[194:195]
	v_pk_mul_f32 v[192:193], v[136:137], v[206:207]
	v_pk_mul_f32 v[194:195], v[134:135], v[204:205]
	v_pk_fma_f32 v[212:213], v[132:133], v[198:199], v[192:193] neg_lo:[0,0,1] neg_hi:[0,0,1]
	v_pk_fma_f32 v[214:215], v[130:131], v[196:197], v[194:195] neg_lo:[0,0,1] neg_hi:[0,0,1]
	v_pk_mul_f32 v[192:193], v[136:137], v[198:199]
	v_pk_mul_f32 v[194:195], v[134:135], v[196:197]
	v_pk_mul_f32 v[218:219], v[176:177], v[202:203] op_sel_hi:[0,1]
	v_pk_fma_f32 v[196:197], v[132:133], v[206:207], v[192:193]
	v_pk_fma_f32 v[198:199], v[130:131], v[204:205], v[194:195]
	v_or_b32_e32 v192, 32, v172
	v_pk_mul_f32 v[194:195], v[176:177], v[208:209] op_sel_hi:[0,1]
	v_pk_mul_f32 v[220:221], v[176:177], v[200:201] op_sel_hi:[0,1]
	v_pk_mul_f32 v[226:227], v[88:89], v[218:219]
	v_pk_mul_f32 v[204:205], v[176:177], v[210:211] op_sel_hi:[0,1]
	v_pk_mul_f32 v[206:207], v[176:177], v[212:213] op_sel_hi:[0,1]
	v_pk_mul_f32 v[222:223], v[176:177], v[196:197] op_sel_hi:[0,1]
	v_pk_mul_f32 v[224:225], v[176:177], v[198:199] op_sel_hi:[0,1]
	v_pk_mul_f32 v[228:229], v[86:87], v[220:221]
	v_pk_fma_f32 v[226:227], v[96:97], v[194:195], v[226:227] neg_lo:[0,0,1] neg_hi:[0,0,1]
	v_pk_mul_f32 v[194:195], v[88:89], v[194:195]
	v_ashrrev_i32_e32 v193, 31, v192
	v_pk_mul_f32 v[216:217], v[176:177], v[214:215] op_sel_hi:[0,1]
	v_pk_fma_f32 v[228:229], v[94:95], v[204:205], v[228:229] neg_lo:[0,0,1] neg_hi:[0,0,1]
	v_pk_mul_f32 v[230:231], v[84:85], v[222:223]
	v_pk_mul_f32 v[232:233], v[82:83], v[224:225]
	v_pk_mul_f32 v[204:205], v[86:87], v[204:205]
	v_pk_fma_f32 v[218:219], v[96:97], v[218:219], v[194:195]
	v_pk_mul_f32 v[194:195], v[84:85], v[206:207]
	v_lshlrev_b64 v[192:193], 10, v[192:193]
	v_pk_fma_f32 v[230:231], v[92:93], v[206:207], v[230:231] neg_lo:[0,0,1] neg_hi:[0,0,1]
	v_pk_fma_f32 v[232:233], v[90:91], v[216:217], v[232:233] neg_lo:[0,0,1] neg_hi:[0,0,1]
	v_pk_fma_f32 v[204:205], v[94:95], v[220:221], v[204:205]
	v_pk_mul_f32 v[206:207], v[82:83], v[216:217]
	v_pk_fma_f32 v[216:217], v[92:93], v[222:223], v[194:195]
	v_lshl_add_u64 v[220:221], v[178:179], 0, v[192:193]
	v_cvt_pk_bf16_f32 v192, v228, v229
	v_cvt_pk_bf16_f32 v193, v226, v227
	v_cvt_pk_bf16_f32 v194, v232, v233
	v_cvt_pk_bf16_f32 v195, v230, v231
	v_pk_fma_f32 v[206:207], v[90:91], v[224:225], v[206:207]
	global_store_dwordx4 v[220:221], v[192:195], off nt
	s_nop 1
	v_cvt_pk_bf16_f32 v192, v204, v205
	v_cvt_pk_bf16_f32 v193, v218, v219
	v_cvt_pk_bf16_f32 v194, v206, v207
	v_cvt_pk_bf16_f32 v195, v216, v217
	global_store_dwordx4 v[220:221], v[192:195], off offset:128 nt
	s_nop 1
	v_pk_mul_f32 v[192:193], v[144:145], v[202:203]
	v_pk_mul_f32 v[194:195], v[142:143], v[200:201]
	v_pk_fma_f32 v[204:205], v[140:141], v[208:209], v[192:193] neg_lo:[0,0,1] neg_hi:[0,0,1]
	v_pk_fma_f32 v[206:207], v[138:139], v[210:211], v[194:195] neg_lo:[0,0,1] neg_hi:[0,0,1]
	v_pk_mul_f32 v[192:193], v[144:145], v[208:209]
	v_pk_mul_f32 v[194:195], v[142:143], v[210:211]
	v_pk_fma_f32 v[202:203], v[140:141], v[202:203], v[192:193]
	v_pk_fma_f32 v[200:201], v[138:139], v[200:201], v[194:195]
	v_pk_mul_f32 v[192:193], v[136:137], v[196:197]
	v_pk_mul_f32 v[194:195], v[134:135], v[198:199]
	v_pk_fma_f32 v[208:209], v[132:133], v[212:213], v[192:193] neg_lo:[0,0,1] neg_hi:[0,0,1]
	v_pk_fma_f32 v[210:211], v[130:131], v[214:215], v[194:195] neg_lo:[0,0,1] neg_hi:[0,0,1]
	v_pk_mul_f32 v[192:193], v[136:137], v[212:213]
	v_pk_mul_f32 v[194:195], v[134:135], v[214:215]
	v_pk_mul_f32 v[218:219], v[176:177], v[202:203] op_sel_hi:[0,1]
	v_pk_fma_f32 v[196:197], v[132:133], v[196:197], v[192:193]
	v_pk_fma_f32 v[198:199], v[130:131], v[198:199], v[194:195]
	v_or_b32_e32 v192, 48, v172
	v_pk_mul_f32 v[194:195], v[176:177], v[204:205] op_sel_hi:[0,1]
	v_pk_mul_f32 v[226:227], v[72:73], v[218:219]
	v_pk_mul_f32 v[214:215], v[176:177], v[208:209] op_sel_hi:[0,1]
	v_pk_mul_f32 v[220:221], v[176:177], v[200:201] op_sel_hi:[0,1]
	v_pk_mul_f32 v[222:223], v[176:177], v[196:197] op_sel_hi:[0,1]
	v_pk_mul_f32 v[224:225], v[176:177], v[198:199] op_sel_hi:[0,1]
	v_pk_fma_f32 v[226:227], v[80:81], v[194:195], v[226:227] neg_lo:[0,0,1] neg_hi:[0,0,1]
	v_pk_mul_f32 v[194:195], v[72:73], v[194:195]
	v_ashrrev_i32_e32 v193, 31, v192
	v_pk_mul_f32 v[212:213], v[176:177], v[206:207] op_sel_hi:[0,1]
	v_pk_mul_f32 v[216:217], v[176:177], v[210:211] op_sel_hi:[0,1]
	v_pk_mul_f32 v[228:229], v[70:71], v[220:221]
	v_pk_mul_f32 v[230:231], v[68:69], v[222:223]
	v_pk_mul_f32 v[232:233], v[66:67], v[224:225]
	v_pk_fma_f32 v[218:219], v[80:81], v[218:219], v[194:195]
; __device__ __forceinline__ unsigned cvt_pk_bf16(float lo, float hi) { unsigned r; asm volatile("v_cvt_pk_bf16_f32 %0, %1, %2" : "=v"(r) : "v"(lo), "v"(hi)); return r; }
;     __device__ __forceinline__ void operator()(const f32x4 (&acc)[2][2][4][2], const pg8::Unit& u, int wr, int wc, int fr, int fq) const {
;     ...
;             for (int k = 0; k < 12; ++k) {
;                 if (k < 4 || k >= 8) {
;                     const int ai = k >> 3, m = k & 3;
;                     const int row = row0 + ai * 128 + m * 16;
;                     const f32x4 c0 = c[0] * osc, c1 = c[1] * osc, s0 = sn[0] * osc, s1 = sn[1] * osc;
;                     const f32x4 a0 = acc[ai][0][m][0], a1 = acc[ai][0][m][1], b0 = acc[ai][1][m][0], b1 = acc[ai][1][m][1];
;                     const f32x4 o10 = a0 * c0 - b0 * s0, o11 = a1 * c1 - b1 * s1, o20 = a0 * s0 + b0 * c0, o21 = a1 * s1 + b1 * c1;
;                     bf16_t* rowp = base + (size_t)row * 512 + col0;
;                     u32x4 w; w.x = cvt_pk_bf16(o10[0], o10[1]); w.y = cvt_pk_bf16(o10[2], o10[3]); w.z = cvt_pk_bf16(o11[0], o11[1]); w.w = cvt_pk_bf16(o11[2], o11[3]);
;                     *(u32x4*)(rowp) = w;
;                     w.x = cvt_pk_bf16(o20[0], o20[1]); w.y = cvt_pk_bf16(o20[2], o20[3]); w.z = cvt_pk_bf16(o21[0], o21[1]); w.w = cvt_pk_bf16(o21[2], o21[3]);
;                     *(u32x4*)(rowp + 64) = w;
;                 }
;                 if (k < 11) {
; #pragma unroll
;                     for (int e = 0; e < 2; ++e) { const f32x4 cn = c[e] * c16[e] - sn[e] * s16[e]; sn[e] = sn[e] * c16[e] + c[e] * s16[e]; c[e] = cn; } }
;             }
	v_pk_mul_f32 v[194:195], v[68:69], v[214:215]
	v_lshlrev_b64 v[192:193], 10, v[192:193]
	v_pk_fma_f32 v[228:229], v[78:79], v[212:213], v[228:229] neg_lo:[0,0,1] neg_hi:[0,0,1]
	v_pk_fma_f32 v[230:231], v[76:77], v[214:215], v[230:231] neg_lo:[0,0,1] neg_hi:[0,0,1]
	v_pk_fma_f32 v[232:233], v[74:75], v[216:217], v[232:233] neg_lo:[0,0,1] neg_hi:[0,0,1]
	v_pk_mul_f32 v[212:213], v[70:71], v[212:213]
	v_pk_mul_f32 v[214:215], v[66:67], v[216:217]
	v_pk_fma_f32 v[216:217], v[76:77], v[222:223], v[194:195]
	v_lshl_add_u64 v[178:179], v[178:179], 0, v[192:193]
	v_cvt_pk_bf16_f32 v192, v228, v229
	v_cvt_pk_bf16_f32 v193, v226, v227
	v_cvt_pk_bf16_f32 v194, v232, v233
	v_cvt_pk_bf16_f32 v195, v230, v231
	v_pk_fma_f32 v[212:213], v[78:79], v[220:221], v[212:213]
	v_pk_fma_f32 v[214:215], v[74:75], v[224:225], v[214:215]
	global_store_dwordx4 v[178:179], v[192:195], off nt
	s_nop 1
	v_cvt_pk_bf16_f32 v192, v212, v213
	v_cvt_pk_bf16_f32 v193, v218, v219
	v_cvt_pk_bf16_f32 v194, v214, v215
	v_cvt_pk_bf16_f32 v195, v216, v217
	global_store_dwordx4 v[178:179], v[192:195], off offset:128 nt
	v_pk_mul_f32 v[178:179], v[144:145], v[202:203]
	s_nop 0
	v_pk_mul_f32 v[194:195], v[144:145], v[204:205]
	v_pk_mul_f32 v[192:193], v[142:143], v[200:201]
	v_pk_fma_f32 v[178:179], v[140:141], v[204:205], v[178:179] neg_lo:[0,0,1] neg_hi:[0,0,1]
	v_pk_mul_f32 v[204:205], v[142:143], v[206:207]
	v_pk_fma_f32 v[194:195], v[140:141], v[202:203], v[194:195]
	v_pk_mul_f32 v[202:203], v[136:137], v[196:197]
	v_pk_fma_f32 v[192:193], v[138:139], v[206:207], v[192:193] neg_lo:[0,0,1] neg_hi:[0,0,1]
	v_pk_fma_f32 v[200:201], v[138:139], v[200:201], v[204:205]
	v_pk_fma_f32 v[202:203], v[132:133], v[208:209], v[202:203] neg_lo:[0,0,1] neg_hi:[0,0,1]
	v_pk_mul_f32 v[206:207], v[136:137], v[208:209]
	v_pk_mul_f32 v[208:209], v[134:135], v[210:211]
	v_pk_mul_f32 v[204:205], v[134:135], v[198:199]
	v_pk_fma_f32 v[196:197], v[132:133], v[196:197], v[206:207]
	v_pk_fma_f32 v[198:199], v[130:131], v[198:199], v[208:209]
	v_pk_mul_f32 v[206:207], v[144:145], v[194:195]
	v_pk_mul_f32 v[208:209], v[142:143], v[200:201]
	v_pk_fma_f32 v[206:207], v[140:141], v[178:179], v[206:207] neg_lo:[0,0,1] neg_hi:[0,0,1]
	v_pk_fma_f32 v[208:209], v[138:139], v[192:193], v[208:209] neg_lo:[0,0,1] neg_hi:[0,0,1]
	v_pk_mul_f32 v[178:179], v[144:145], v[178:179]
	v_pk_mul_f32 v[192:193], v[142:143], v[192:193]
	v_pk_fma_f32 v[204:205], v[130:131], v[210:211], v[204:205] neg_lo:[0,0,1] neg_hi:[0,0,1]
	v_pk_fma_f32 v[178:179], v[140:141], v[194:195], v[178:179]
	v_pk_fma_f32 v[192:193], v[138:139], v[200:201], v[192:193]
	v_pk_mul_f32 v[194:195], v[136:137], v[196:197]
	v_pk_mul_f32 v[200:201], v[134:135], v[198:199]
	v_pk_fma_f32 v[194:195], v[132:133], v[202:203], v[194:195] neg_lo:[0,0,1] neg_hi:[0,0,1]
	v_pk_fma_f32 v[200:201], v[130:131], v[204:205], v[200:201] neg_lo:[0,0,1] neg_hi:[0,0,1]
	v_pk_mul_f32 v[202:203], v[136:137], v[202:203]
	v_pk_mul_f32 v[204:205], v[134:135], v[204:205]
	v_pk_fma_f32 v[196:197], v[132:133], v[196:197], v[202:203]
	v_pk_fma_f32 v[198:199], v[130:131], v[198:199], v[204:205]
	v_pk_mul_f32 v[202:203], v[144:145], v[178:179]
	v_pk_mul_f32 v[204:205], v[142:143], v[192:193]
	v_pk_fma_f32 v[202:203], v[140:141], v[206:207], v[202:203] neg_lo:[0,0,1] neg_hi:[0,0,1]
	v_pk_fma_f32 v[204:205], v[138:139], v[208:209], v[204:205] neg_lo:[0,0,1] neg_hi:[0,0,1]
	v_pk_mul_f32 v[206:207], v[144:145], v[206:207]
	v_pk_mul_f32 v[208:209], v[142:143], v[208:209]
	v_pk_fma_f32 v[178:179], v[140:141], v[178:179], v[206:207]
	v_pk_fma_f32 v[192:193], v[138:139], v[192:193], v[208:209]
	v_pk_mul_f32 v[206:207], v[136:137], v[196:197]
	v_pk_mul_f32 v[208:209], v[134:135], v[198:199]
	v_pk_fma_f32 v[206:207], v[132:133], v[194:195], v[206:207] neg_lo:[0,0,1] neg_hi:[0,0,1]
	v_pk_fma_f32 v[208:209], v[130:131], v[200:201], v[208:209] neg_lo:[0,0,1] neg_hi:[0,0,1]
	v_pk_mul_f32 v[194:195], v[136:137], v[194:195]
	v_pk_mul_f32 v[200:201], v[134:135], v[200:201]
	v_pk_fma_f32 v[194:195], v[132:133], v[196:197], v[194:195]
	v_pk_fma_f32 v[196:197], v[130:131], v[198:199], v[200:201]
	v_pk_mul_f32 v[198:199], v[144:145], v[178:179]
	v_pk_mul_f32 v[200:201], v[142:143], v[192:193]
	v_pk_fma_f32 v[198:199], v[140:141], v[202:203], v[198:199] neg_lo:[0,0,1] neg_hi:[0,0,1]
	v_pk_fma_f32 v[200:201], v[138:139], v[204:205], v[200:201] neg_lo:[0,0,1] neg_hi:[0,0,1]
	v_pk_mul_f32 v[202:203], v[144:145], v[202:203]
	v_pk_mul_f32 v[204:205], v[142:143], v[204:205]
	v_pk_fma_f32 v[178:179], v[140:141], v[178:179], v[202:203]
	v_pk_fma_f32 v[192:193], v[138:139], v[192:193], v[204:205]
	v_pk_mul_f32 v[202:203], v[136:137], v[194:195]
	v_pk_mul_f32 v[204:205], v[134:135], v[196:197]
	v_pk_fma_f32 v[202:203], v[132:133], v[206:207], v[202:203] neg_lo:[0,0,1] neg_hi:[0,0,1]
	v_pk_fma_f32 v[204:205], v[130:131], v[208:209], v[204:205] neg_lo:[0,0,1] neg_hi:[0,0,1]
	v_pk_mul_f32 v[206:207], v[136:137], v[206:207]
	v_pk_mul_f32 v[208:209], v[134:135], v[208:209]
	v_pk_fma_f32 v[194:195], v[132:133], v[194:195], v[206:207]
	v_pk_fma_f32 v[196:197], v[130:131], v[196:197], v[208:209]
	v_pk_mul_f32 v[206:207], v[144:145], v[178:179]
	v_pk_mul_f32 v[208:209], v[142:143], v[192:193]
	v_pk_fma_f32 v[206:207], v[140:141], v[198:199], v[206:207] neg_lo:[0,0,1] neg_hi:[0,0,1]
	v_pk_fma_f32 v[208:209], v[138:139], v[200:201], v[208:209] neg_lo:[0,0,1] neg_hi:[0,0,1]
	v_pk_mul_f32 v[198:199], v[144:145], v[198:199]
	v_pk_mul_f32 v[200:201], v[142:143], v[200:201]
	v_pk_fma_f32 v[178:179], v[140:141], v[178:179], v[198:199]
	v_pk_fma_f32 v[198:199], v[138:139], v[192:193], v[200:201]
	v_pk_mul_f32 v[192:193], v[136:137], v[194:195]
; __device__ __forceinline__ unsigned cvt_pk_bf16(float lo, float hi) { unsigned r; asm volatile("v_cvt_pk_bf16_f32 %0, %1, %2" : "=v"(r) : "v"(lo), "v"(hi)); return r; }
;     __device__ __forceinline__ void operator()(const f32x4 (&acc)[2][2][4][2], const pg8::Unit& u, int wr, int wc, int fr, int fq) const {
;     ...
;             for (int k = 0; k < 12; ++k) {
;                 if (k < 4 || k >= 8) {
;                     const int ai = k >> 3, m = k & 3;
;                     const int row = row0 + ai * 128 + m * 16;
;                     const f32x4 c0 = c[0] * osc, c1 = c[1] * osc, s0 = sn[0] * osc, s1 = sn[1] * osc;
;                     const f32x4 a0 = acc[ai][0][m][0], a1 = acc[ai][0][m][1], b0 = acc[ai][1][m][0], b1 = acc[ai][1][m][1];
;                     const f32x4 o10 = a0 * c0 - b0 * s0, o11 = a1 * c1 - b1 * s1, o20 = a0 * s0 + b0 * c0, o21 = a1 * s1 + b1 * c1;
;                     bf16_t* rowp = base + (size_t)row * 512 + col0;
;                     u32x4 w; w.x = cvt_pk_bf16(o10[0], o10[1]); w.y = cvt_pk_bf16(o10[2], o10[3]); w.z = cvt_pk_bf16(o11[0], o11[1]); w.w = cvt_pk_bf16(o11[2], o11[3]);
;                     *(u32x4*)(rowp) = w;
;                     w.x = cvt_pk_bf16(o20[0], o20[1]); w.y = cvt_pk_bf16(o20[2], o20[3]); w.z = cvt_pk_bf16(o21[0], o21[1]); w.w = cvt_pk_bf16(o21[2], o21[3]);
;                     *(u32x4*)(rowp + 64) = w;
;                 }
;                 if (k < 11) {
; #pragma unroll
;                     for (int e = 0; e < 2; ++e) { const f32x4 cn = c[e] * c16[e] - sn[e] * s16[e]; sn[e] = sn[e] * c16[e] + c[e] * s16[e]; c[e] = cn; } }
;             }
	v_pk_mul_f32 v[200:201], v[134:135], v[196:197]
	v_pk_fma_f32 v[210:211], v[132:133], v[202:203], v[192:193] neg_lo:[0,0,1] neg_hi:[0,0,1]
	v_pk_mul_f32 v[192:193], v[136:137], v[202:203]
	v_pk_mul_f32 v[202:203], v[134:135], v[204:205]
	v_pk_mul_f32 v[216:217], v[176:177], v[198:199] op_sel_hi:[0,1]
	v_pk_fma_f32 v[200:201], v[130:131], v[204:205], v[200:201] neg_lo:[0,0,1] neg_hi:[0,0,1]
	v_pk_fma_f32 v[204:205], v[132:133], v[194:195], v[192:193]
	v_pk_fma_f32 v[196:197], v[130:131], v[196:197], v[202:203]
	v_pk_mul_f32 v[194:195], v[176:177], v[208:209] op_sel_hi:[0,1]
	v_pk_mul_f32 v[214:215], v[176:177], v[178:179] op_sel_hi:[0,1]
	v_pk_mul_f32 v[224:225], v[54:55], v[216:217]
	v_pk_mul_f32 v[192:193], v[176:177], v[206:207] op_sel_hi:[0,1]
	v_pk_mul_f32 v[212:213], v[176:177], v[200:201] op_sel_hi:[0,1]
	v_pk_mul_f32 v[220:221], v[176:177], v[196:197] op_sel_hi:[0,1]
	v_pk_mul_f32 v[222:223], v[56:57], v[214:215]
	v_pk_fma_f32 v[224:225], v[62:63], v[194:195], v[224:225] neg_lo:[0,0,1] neg_hi:[0,0,1]
	v_pk_mul_f32 v[194:195], v[54:55], v[194:195]
	v_pk_mul_f32 v[202:203], v[176:177], v[210:211] op_sel_hi:[0,1]
	v_pk_mul_f32 v[218:219], v[176:177], v[204:205] op_sel_hi:[0,1]
	v_pk_fma_f32 v[222:223], v[64:65], v[192:193], v[222:223] neg_lo:[0,0,1] neg_hi:[0,0,1]
	v_pk_mul_f32 v[228:229], v[50:51], v[220:221]
	v_pk_mul_f32 v[192:193], v[56:57], v[192:193]
	v_pk_fma_f32 v[216:217], v[62:63], v[216:217], v[194:195]
	v_pk_mul_f32 v[194:195], v[50:51], v[212:213]
	v_pk_mul_f32 v[226:227], v[52:53], v[218:219]
	v_pk_fma_f32 v[228:229], v[58:59], v[212:213], v[228:229] neg_lo:[0,0,1] neg_hi:[0,0,1]
	v_pk_fma_f32 v[214:215], v[64:65], v[214:215], v[192:193]
	v_pk_mul_f32 v[192:193], v[52:53], v[202:203]
	v_pk_fma_f32 v[212:213], v[58:59], v[220:221], v[194:195]
	v_add_co_u32_e32 v220, vcc, s87, v174
	v_pk_fma_f32 v[226:227], v[60:61], v[202:203], v[226:227] neg_lo:[0,0,1] neg_hi:[0,0,1]
	v_pk_fma_f32 v[202:203], v[60:61], v[218:219], v[192:193]
	v_cvt_pk_bf16_f32 v192, v224, v225
	v_cvt_pk_bf16_f32 v193, v222, v223
	v_cvt_pk_bf16_f32 v194, v228, v229
	v_cvt_pk_bf16_f32 v195, v226, v227
	v_addc_co_u32_e32 v221, vcc, 0, v175, vcc
	v_lshl_add_u64 v[218:219], v[174:175], 0, s[16:17]
	global_store_dwordx4 v[220:221], v[192:195], off nt
	s_nop 1
	v_cvt_pk_bf16_f32 v192, v216, v217
	v_cvt_pk_bf16_f32 v193, v214, v215
	v_cvt_pk_bf16_f32 v194, v212, v213
	v_cvt_pk_bf16_f32 v195, v202, v203
	global_store_dwordx4 v[218:219], v[192:195], off offset:128 nt
	s_nop 1
	v_pk_mul_f32 v[194:195], v[142:143], v[198:199]
	v_pk_mul_f32 v[192:193], v[144:145], v[178:179]
	v_pk_fma_f32 v[212:213], v[138:139], v[208:209], v[194:195] neg_lo:[0,0,1] neg_hi:[0,0,1]
	v_pk_mul_f32 v[194:195], v[142:143], v[208:209]
	v_pk_fma_f32 v[202:203], v[140:141], v[206:207], v[192:193] neg_lo:[0,0,1] neg_hi:[0,0,1]
	v_pk_mul_f32 v[192:193], v[144:145], v[206:207]
	v_pk_fma_f32 v[198:199], v[138:139], v[198:199], v[194:195]
	v_pk_mul_f32 v[194:195], v[134:135], v[196:197]
	v_pk_fma_f32 v[178:179], v[140:141], v[178:179], v[192:193]
	v_pk_mul_f32 v[192:193], v[136:137], v[204:205]
	v_pk_fma_f32 v[208:209], v[130:131], v[200:201], v[194:195] neg_lo:[0,0,1] neg_hi:[0,0,1]
	v_pk_mul_f32 v[194:195], v[134:135], v[200:201]
	v_pk_mul_f32 v[216:217], v[176:177], v[198:199] op_sel_hi:[0,1]
	v_pk_fma_f32 v[206:207], v[132:133], v[210:211], v[192:193] neg_lo:[0,0,1] neg_hi:[0,0,1]
	v_pk_mul_f32 v[192:193], v[136:137], v[210:211]
	v_pk_fma_f32 v[196:197], v[130:131], v[196:197], v[194:195]
	v_pk_mul_f32 v[194:195], v[176:177], v[212:213] op_sel_hi:[0,1]
	v_pk_mul_f32 v[214:215], v[176:177], v[178:179] op_sel_hi:[0,1]
	v_pk_mul_f32 v[224:225], v[38:39], v[216:217]
	v_pk_fma_f32 v[200:201], v[132:133], v[204:205], v[192:193]
	v_pk_mul_f32 v[192:193], v[176:177], v[202:203] op_sel_hi:[0,1]
	v_pk_mul_f32 v[210:211], v[176:177], v[208:209] op_sel_hi:[0,1]
	v_pk_mul_f32 v[220:221], v[176:177], v[196:197] op_sel_hi:[0,1]
	v_pk_mul_f32 v[222:223], v[40:41], v[214:215]
	v_pk_fma_f32 v[224:225], v[46:47], v[194:195], v[224:225] neg_lo:[0,0,1] neg_hi:[0,0,1]
	v_pk_mul_f32 v[194:195], v[38:39], v[194:195]
	v_pk_mul_f32 v[204:205], v[176:177], v[206:207] op_sel_hi:[0,1]
	v_pk_mul_f32 v[218:219], v[176:177], v[200:201] op_sel_hi:[0,1]
	v_pk_fma_f32 v[222:223], v[48:49], v[192:193], v[222:223] neg_lo:[0,0,1] neg_hi:[0,0,1]
	v_pk_mul_f32 v[228:229], v[34:35], v[220:221]
	v_pk_mul_f32 v[192:193], v[40:41], v[192:193]
	v_pk_fma_f32 v[216:217], v[46:47], v[216:217], v[194:195]
	v_pk_mul_f32 v[194:195], v[34:35], v[210:211]
	v_pk_mul_f32 v[226:227], v[36:37], v[218:219]
	v_pk_fma_f32 v[228:229], v[42:43], v[210:211], v[228:229] neg_lo:[0,0,1] neg_hi:[0,0,1]
	v_pk_fma_f32 v[214:215], v[48:49], v[214:215], v[192:193]
	v_pk_mul_f32 v[192:193], v[36:37], v[204:205]
	v_pk_fma_f32 v[210:211], v[42:43], v[220:221], v[194:195]
	v_add_co_u32_e32 v220, vcc, s88, v174
	v_pk_fma_f32 v[226:227], v[44:45], v[204:205], v[226:227] neg_lo:[0,0,1] neg_hi:[0,0,1]
	v_pk_fma_f32 v[204:205], v[44:45], v[218:219], v[192:193]
	v_cvt_pk_bf16_f32 v192, v224, v225
	v_cvt_pk_bf16_f32 v193, v222, v223
	v_cvt_pk_bf16_f32 v194, v228, v229
	v_cvt_pk_bf16_f32 v195, v226, v227
	v_addc_co_u32_e32 v221, vcc, 0, v175, vcc
	v_lshl_add_u64 v[218:219], v[174:175], 0, s[18:19]
	global_store_dwordx4 v[220:221], v[192:195], off nt
	s_nop 1
	v_cvt_pk_bf16_f32 v192, v216, v217
	v_cvt_pk_bf16_f32 v193, v214, v215
	v_cvt_pk_bf16_f32 v194, v210, v211
	v_cvt_pk_bf16_f32 v195, v204, v205
	global_store_dwordx4 v[218:219], v[192:195], off offset:128 nt
	s_nop 1
	v_pk_mul_f32 v[194:195], v[142:143], v[198:199]
	v_pk_mul_f32 v[192:193], v[144:145], v[178:179]
; __device__ __forceinline__ unsigned cvt_pk_bf16(float lo, float hi) { unsigned r; asm volatile("v_cvt_pk_bf16_f32 %0, %1, %2" : "=v"(r) : "v"(lo), "v"(hi)); return r; }
;     __device__ __forceinline__ void operator()(const f32x4 (&acc)[2][2][4][2], const pg8::Unit& u, int wr, int wc, int fr, int fq) const {
;     ...
;             for (int k = 0; k < 12; ++k) {
;                 if (k < 4 || k >= 8) {
;                     const int ai = k >> 3, m = k & 3;
;                     const int row = row0 + ai * 128 + m * 16;
;                     const f32x4 c0 = c[0] * osc, c1 = c[1] * osc, s0 = sn[0] * osc, s1 = sn[1] * osc;
;                     const f32x4 a0 = acc[ai][0][m][0], a1 = acc[ai][0][m][1], b0 = acc[ai][1][m][0], b1 = acc[ai][1][m][1];
;                     const f32x4 o10 = a0 * c0 - b0 * s0, o11 = a1 * c1 - b1 * s1, o20 = a0 * s0 + b0 * c0, o21 = a1 * s1 + b1 * c1;
;                     bf16_t* rowp = base + (size_t)row * 512 + col0;
;                     u32x4 w; w.x = cvt_pk_bf16(o10[0], o10[1]); w.y = cvt_pk_bf16(o10[2], o10[3]); w.z = cvt_pk_bf16(o11[0], o11[1]); w.w = cvt_pk_bf16(o11[2], o11[3]);
;                     *(u32x4*)(rowp) = w;
;                     w.x = cvt_pk_bf16(o20[0], o20[1]); w.y = cvt_pk_bf16(o20[2], o20[3]); w.z = cvt_pk_bf16(o21[0], o21[1]); w.w = cvt_pk_bf16(o21[2], o21[3]);
;                     *(u32x4*)(rowp + 64) = w;
;                 }
;                 if (k < 11) {
; #pragma unroll
;                     for (int e = 0; e < 2; ++e) { const f32x4 cn = c[e] * c16[e] - sn[e] * s16[e]; sn[e] = sn[e] * c16[e] + c[e] * s16[e]; c[e] = cn; } }
;             }
	v_pk_fma_f32 v[210:211], v[138:139], v[212:213], v[194:195] neg_lo:[0,0,1] neg_hi:[0,0,1]
	v_pk_mul_f32 v[194:195], v[142:143], v[212:213]
	v_pk_fma_f32 v[204:205], v[140:141], v[202:203], v[192:193] neg_lo:[0,0,1] neg_hi:[0,0,1]
	v_pk_mul_f32 v[192:193], v[144:145], v[202:203]
	v_pk_fma_f32 v[198:199], v[138:139], v[198:199], v[194:195]
	v_pk_mul_f32 v[194:195], v[134:135], v[196:197]
	v_pk_fma_f32 v[178:179], v[140:141], v[178:179], v[192:193]
	v_pk_mul_f32 v[192:193], v[136:137], v[200:201]
	v_pk_fma_f32 v[212:213], v[130:131], v[208:209], v[194:195] neg_lo:[0,0,1] neg_hi:[0,0,1]
	v_pk_mul_f32 v[194:195], v[134:135], v[208:209]
	v_pk_mul_f32 v[216:217], v[176:177], v[198:199] op_sel_hi:[0,1]
	v_pk_fma_f32 v[202:203], v[132:133], v[206:207], v[192:193] neg_lo:[0,0,1] neg_hi:[0,0,1]
	v_pk_mul_f32 v[192:193], v[136:137], v[206:207]
	v_pk_fma_f32 v[196:197], v[130:131], v[196:197], v[194:195]
	v_pk_mul_f32 v[194:195], v[176:177], v[210:211] op_sel_hi:[0,1]
	v_pk_mul_f32 v[214:215], v[176:177], v[178:179] op_sel_hi:[0,1]
	v_pk_mul_f32 v[224:225], v[22:23], v[216:217]
	v_pk_fma_f32 v[200:201], v[132:133], v[200:201], v[192:193]
	v_pk_mul_f32 v[192:193], v[176:177], v[204:205] op_sel_hi:[0,1]
	v_pk_mul_f32 v[208:209], v[176:177], v[212:213] op_sel_hi:[0,1]
	v_pk_mul_f32 v[220:221], v[176:177], v[196:197] op_sel_hi:[0,1]
	v_pk_mul_f32 v[222:223], v[24:25], v[214:215]
	v_pk_fma_f32 v[224:225], v[30:31], v[194:195], v[224:225] neg_lo:[0,0,1] neg_hi:[0,0,1]
	v_pk_mul_f32 v[194:195], v[22:23], v[194:195]
	v_pk_mul_f32 v[206:207], v[176:177], v[202:203] op_sel_hi:[0,1]
	v_pk_mul_f32 v[218:219], v[176:177], v[200:201] op_sel_hi:[0,1]
	v_pk_fma_f32 v[222:223], v[32:33], v[192:193], v[222:223] neg_lo:[0,0,1] neg_hi:[0,0,1]
	v_pk_mul_f32 v[228:229], v[18:19], v[220:221]
	v_pk_mul_f32 v[192:193], v[24:25], v[192:193]
	v_pk_fma_f32 v[216:217], v[30:31], v[216:217], v[194:195]
	v_pk_mul_f32 v[194:195], v[18:19], v[208:209]
	v_pk_mul_f32 v[226:227], v[20:21], v[218:219]
	v_pk_fma_f32 v[228:229], v[26:27], v[208:209], v[228:229] neg_lo:[0,0,1] neg_hi:[0,0,1]
	v_pk_fma_f32 v[214:215], v[32:33], v[214:215], v[192:193]
	v_pk_mul_f32 v[192:193], v[20:21], v[206:207]
	v_pk_fma_f32 v[208:209], v[26:27], v[220:221], v[194:195]
	v_add_co_u32_e32 v220, vcc, s89, v174
	v_pk_fma_f32 v[226:227], v[28:29], v[206:207], v[226:227] neg_lo:[0,0,1] neg_hi:[0,0,1]
	v_pk_fma_f32 v[206:207], v[28:29], v[218:219], v[192:193]
	v_cvt_pk_bf16_f32 v192, v224, v225
	v_cvt_pk_bf16_f32 v193, v222, v223
	v_cvt_pk_bf16_f32 v194, v228, v229
	v_cvt_pk_bf16_f32 v195, v226, v227
	v_addc_co_u32_e32 v221, vcc, 0, v175, vcc
	v_lshl_add_u64 v[218:219], v[174:175], 0, s[20:21]
	global_store_dwordx4 v[220:221], v[192:195], off nt
	s_nop 1
	v_cvt_pk_bf16_f32 v192, v216, v217
	v_cvt_pk_bf16_f32 v193, v214, v215
	v_cvt_pk_bf16_f32 v194, v208, v209
	v_cvt_pk_bf16_f32 v195, v206, v207
	global_store_dwordx4 v[218:219], v[192:195], off offset:128 nt
	s_nop 1
	v_pk_mul_f32 v[192:193], v[144:145], v[178:179]
	v_pk_mul_f32 v[194:195], v[142:143], v[198:199]
	v_pk_mul_f32 v[144:145], v[144:145], v[204:205]
	v_pk_mul_f32 v[142:143], v[142:143], v[210:211]
	v_pk_fma_f32 v[192:193], v[140:141], v[204:205], v[192:193] neg_lo:[0,0,1] neg_hi:[0,0,1]
	v_pk_fma_f32 v[194:195], v[138:139], v[210:211], v[194:195] neg_lo:[0,0,1] neg_hi:[0,0,1]
	v_pk_fma_f32 v[140:141], v[140:141], v[178:179], v[144:145]
	v_pk_fma_f32 v[138:139], v[138:139], v[198:199], v[142:143]
	v_pk_mul_f32 v[142:143], v[136:137], v[200:201]
	v_pk_mul_f32 v[144:145], v[134:135], v[196:197]
	v_pk_mul_f32 v[136:137], v[136:137], v[202:203]
	v_pk_mul_f32 v[134:135], v[134:135], v[212:213]
	v_pk_fma_f32 v[142:143], v[132:133], v[202:203], v[142:143] neg_lo:[0,0,1] neg_hi:[0,0,1]
	v_pk_fma_f32 v[144:145], v[130:131], v[212:213], v[144:145] neg_lo:[0,0,1] neg_hi:[0,0,1]
	v_pk_fma_f32 v[132:133], v[132:133], v[200:201], v[136:137]
	v_pk_fma_f32 v[130:131], v[130:131], v[196:197], v[134:135]
	v_pk_mul_f32 v[140:141], v[176:177], v[140:141] op_sel_hi:[0,1]
	v_pk_mul_f32 v[138:139], v[176:177], v[138:139] op_sel_hi:[0,1]
	v_pk_mul_f32 v[134:135], v[176:177], v[192:193] op_sel_hi:[0,1]
	v_pk_mul_f32 v[136:137], v[176:177], v[194:195] op_sel_hi:[0,1]
	v_pk_mul_f32 v[142:143], v[176:177], v[142:143] op_sel_hi:[0,1]
	v_pk_mul_f32 v[144:145], v[176:177], v[144:145] op_sel_hi:[0,1]
	v_pk_mul_f32 v[132:133], v[176:177], v[132:133] op_sel_hi:[0,1]
	v_pk_mul_f32 v[130:131], v[176:177], v[130:131] op_sel_hi:[0,1]
	v_pk_mul_f32 v[176:177], v[8:9], v[140:141]
	v_pk_mul_f32 v[178:179], v[6:7], v[138:139]
	v_pk_fma_f32 v[176:177], v[16:17], v[134:135], v[176:177] neg_lo:[0,0,1] neg_hi:[0,0,1]
	v_pk_fma_f32 v[178:179], v[14:15], v[136:137], v[178:179] neg_lo:[0,0,1] neg_hi:[0,0,1]
	v_pk_mul_f32 v[194:195], v[2:3], v[130:131]
	v_pk_mul_f32 v[134:135], v[8:9], v[134:135]
	v_pk_mul_f32 v[136:137], v[6:7], v[136:137]
	v_pk_mul_f32 v[192:193], v[4:5], v[132:133]
	v_pk_fma_f32 v[194:195], v[10:11], v[144:145], v[194:195] neg_lo:[0,0,1] neg_hi:[0,0,1]
	v_pk_fma_f32 v[134:135], v[16:17], v[140:141], v[134:135]
	v_pk_fma_f32 v[136:137], v[14:15], v[138:139], v[136:137]
	v_pk_mul_f32 v[138:139], v[4:5], v[142:143]
	v_pk_mul_f32 v[140:141], v[2:3], v[144:145]
	v_add_co_u32_e32 v144, vcc, s90, v174
	v_pk_fma_f32 v[192:193], v[12:13], v[142:143], v[192:193] neg_lo:[0,0,1] neg_hi:[0,0,1]
	v_pk_fma_f32 v[138:139], v[12:13], v[132:133], v[138:139]
	v_pk_fma_f32 v[140:141], v[10:11], v[130:131], v[140:141]
	v_lshl_add_u64 v[142:143], v[174:175], 0, s[24:25]
	v_cvt_pk_bf16_f32 v130, v178, v179
	v_cvt_pk_bf16_f32 v131, v176, v177
	v_cvt_pk_bf16_f32 v132, v194, v195
	v_cvt_pk_bf16_f32 v133, v192, v193
	v_addc_co_u32_e32 v145, vcc, 0, v175, vcc
	global_store_dwordx4 v[144:145], v[130:133], off nt
	s_nop 1
	v_cvt_pk_bf16_f32 v130, v136, v137
	v_cvt_pk_bf16_f32 v131, v134, v135
	v_cvt_pk_bf16_f32 v132, v140, v141
	v_cvt_pk_bf16_f32 v133, v138, v139
	global_store_dwordx4 v[142:143], v[130:133], off offset:128 nt

; __device__ __forceinline__ unsigned cvt_pk_bf16(float lo, float hi) { unsigned r; asm volatile("v_cvt_pk_bf16_f32 %0, %1, %2" : "=v"(r) : "v"(lo), "v"(hi)); return r; }
;     __device__ __forceinline__ void operator()(const f32x4 (&acc)[2][2][4][2], const pg8::Unit& u, int wr, int wc, int fr, int fq) const {
;     ...
;         if (sec <= 1) {
;             const float* gn = sec == 0 ? qg : kg; const float osc = sec == 0 ? 0.125f * LOG2E : 1.f;
;             f32x4 g[2][2];
; #pragma unroll
;             for (int bj = 0; bj < 2; ++bj)
; #pragma unroll
;                 for (int n = 0; n < 2; ++n) g[bj][n] = *(const f32x4*)(gn + 32 * bj + 8 * fq + 4 * n);
;             const int col0 = 256 * half + 64 * wc + 8 * fq;
; #pragma unroll
;             for (int ai = 0; ai < 2; ++ai)
; #pragma unroll
;                 for (int m = 0; m < 4; ++m) {
;                     float ss = 0.f;
; #pragma unroll
;                     for (int bj = 0; bj < 2; ++bj)
; #pragma unroll
;                         for (int n = 0; n < 2; ++n) { const f32x4 x = acc[ai][bj][m][n]; ss += (x[0] * x[0] + x[1] * x[1]) + (x[2] * x[2] + x[3] * x[3]); }
;                     ss = row4_sum(ss);
;                     const float r = rsqrtf(ss * (1.f / 64.f) + EPS) * osc;
;                     bf16_t* rowp = base + (size_t)(row0 + ai * 128 + m * 16) * 512 + col0;
; #pragma unroll
;                     for (int bj = 0; bj < 2; ++bj) { const f32x4 v0 = acc[ai][bj][m][0] * r * g[bj][0], v1 = acc[ai][bj][m][1] * r * g[bj][1];
;                         u32x4 w; w.x = cvt_pk_bf16(v0[0], v0[1]); w.y = cvt_pk_bf16(v0[2], v0[3]); w.z = cvt_pk_bf16(v1[0], v1[1]); w.w = cvt_pk_bf16(v1[2], v1[3]);
;                         *(u32x4*)(rowp + 32 * bj) = w; }
;                 }
.LBB0_205:
	s_cmp_lt_u32 s46, 2
	s_cselect_b64 vcc, -1, 0
	s_and_b64 s[4:5], vcc, exec
	s_cselect_b32 s5, s53, s55
	s_cselect_b32 s4, s52, s54
	global_load_dwordx4 v[142:145], v187, s[4:5]
	global_load_dwordx4 v[138:141], v187, s[4:5] offset:16
	global_load_dwordx4 v[134:137], v187, s[4:5] offset:128
	global_load_dwordx4 v[130:133], v187, s[4:5] offset:144
	s_mov_b32 s4, 0x55555555
	s_mov_b32 s5, 0x55555555
	v_and_b32_e32 v218, 1, v172
	v_sub_u32_e32 v219, 0, v218
	v_and_b32_e32 v218, 0xfffffc40, v219
	v_mul_f32_e32 v176, v127, v127
	v_mul_f32_e32 v177, v129, v129
	v_mul_f32_e32 v179, v123, v123
	v_mul_f32_e32 v191, v125, v125
	v_mul_f32_e32 v192, v119, v119
	v_mul_f32_e32 v193, v121, v121
	v_ashrrev_i32_e32 v173, 31, v172
	v_fmac_f32_e32 v176, v126, v126
	v_fmac_f32_e32 v177, v128, v128
	v_fmac_f32_e32 v179, v122, v122
	v_fmac_f32_e32 v191, v124, v124
	v_mul_f32_e32 v194, v115, v115
	v_mul_f32_e32 v195, v117, v117
	v_fmac_f32_e32 v192, v118, v118
	v_fmac_f32_e32 v193, v120, v120
	v_lshlrev_b64 v[174:175], 10, v[172:173]
	v_add_f32_e32 v173, v176, v177
	v_add_f32_e32 v176, v179, v191
	v_fmac_f32_e32 v194, v114, v114
	v_fmac_f32_e32 v195, v116, v116
	v_add_f32_e32 v177, v192, v193
	v_add_f32_e32 v173, v173, v176
	v_add_f32_e32 v179, v194, v195
	v_add_f32_e32 v173, v173, v177
	v_add_f32_e32 v173, v173, v179
	v_mov_b32_e32 v176, v173
	s_nop 1
	v_permlane16_swap_b32_e32 v173, v176
	v_add_f32_e32 v173, v173, v176
	v_mov_b32_e32 v176, v173
	s_nop 1
	v_permlane32_swap_b32_e32 v173, v176
	v_add_f32_e32 v173, v173, v176
	v_fmamk_f32 v173, v173, 0x3c800000, v188
	v_cndmask_b32_e32 v178, 1.0, v190, vcc
	v_mul_f32_e32 v176, 0x4b800000, v173
	v_cmp_gt_f32_e32 vcc, s91, v173
	v_lshlrev_b32_e32 v154, 1, v182
	v_lshl_or_b32 v154, s27, 9, v154
	v_cndmask_b32_e32 v173, v173, v176, vcc
	v_rsq_f32_e32 v173, v173
	v_lshl_add_u64 v[176:177], s[48:49], 0, v[154:155]
	v_mul_f32_e32 v196, v111, v111
	v_mul_f32_e32 v197, v113, v113
	v_mul_f32_e32 v154, 0x45800000, v173
	v_cndmask_b32_e32 v154, v173, v154, vcc
	v_mul_f32_e32 v154, v178, v154
	v_pk_mul_f32 v[126:127], v[126:127], v[154:155] op_sel_hi:[1,0]
	v_pk_mul_f32 v[128:129], v[128:129], v[154:155] op_sel_hi:[1,0]
	v_pk_mul_f32 v[122:123], v[122:123], v[154:155] op_sel_hi:[1,0]
	v_pk_mul_f32 v[124:125], v[124:125], v[154:155] op_sel_hi:[1,0]
	v_pk_mul_f32 v[118:119], v[118:119], v[154:155] op_sel_hi:[1,0]
	v_pk_mul_f32 v[114:115], v[114:115], v[154:155] op_sel_hi:[1,0]
	v_pk_mul_f32 v[116:117], v[116:117], v[154:155] op_sel_hi:[1,0]
	v_mul_f32_e32 v198, v107, v107
	v_mul_f32_e32 v199, v109, v109
	v_lshl_add_u64 v[174:175], v[176:177], 0, v[174:175]
	v_fmac_f32_e32 v196, v110, v110
	v_fmac_f32_e32 v197, v112, v112
	v_fmac_f32_e32 v198, v106, v106
	v_fmac_f32_e32 v199, v108, v108
	v_add_f32_e32 v179, v196, v197
	v_pk_mul_f32 v[120:121], v[120:121], v[154:155] op_sel_hi:[1,0]
	s_waitcnt vmcnt(0)
	v_pk_mul_f32 v[128:129], v[144:145], v[128:129]
	v_pk_mul_f32 v[126:127], v[142:143], v[126:127]
	v_pk_mul_f32 v[124:125], v[140:141], v[124:125]
	v_pk_mul_f32 v[122:123], v[138:139], v[122:123]
	v_pk_mul_f32 v[118:119], v[134:135], v[118:119]
	v_pk_mul_f32 v[192:193], v[132:133], v[116:117]
	v_pk_mul_f32 v[194:195], v[130:131], v[114:115]
	v_cvt_pk_bf16_f32 v114, v126, v127
	v_cvt_pk_bf16_f32 v115, v128, v129
	v_cvt_pk_bf16_f32 v116, v122, v123
	v_cvt_pk_bf16_f32 v117, v124, v125
	v_mov_b32_e32 v200, v114
	v_mov_b32_e32 v201, v115
	v_mov_b32_e32 v202, v116
	v_mov_b32_e32 v203, v117
	v_lshl_add_u64 v[216:217], v[174:175], 0, v[218:219]
	v_pk_mul_f32 v[120:121], v[136:137], v[120:121]
	s_nop 0
	v_cvt_pk_bf16_f32 v114, v118, v119
	v_mul_f32_e32 v117, v103, v103
	v_mul_f32_e32 v118, v105, v105
	v_add_f32_e32 v116, v198, v199
	v_fmac_f32_e32 v117, v102, v102
	v_fmac_f32_e32 v118, v104, v104
	v_add_f32_e32 v116, v179, v116
	v_add_f32_e32 v117, v117, v118
	v_add_f32_e32 v116, v116, v117
	v_mul_f32_e32 v117, v99, v99
	v_mul_f32_e32 v118, v101, v101
	v_fmac_f32_e32 v117, v98, v98
	v_fmac_f32_e32 v118, v100, v100
	v_add_f32_e32 v117, v117, v118
	v_add_f32_e32 v116, v116, v117
	v_mov_b32_e32 v117, v116
	s_nop 1
	v_permlane16_swap_b32_e32 v116, v117
	v_add_f32_e32 v116, v116, v117
	v_mov_b32_e32 v117, v116
	s_nop 1
	v_permlane32_swap_b32_e32 v116, v117
	v_add_f32_e32 v116, v116, v117
	v_fmamk_f32 v116, v116, 0x3c800000, v188
	v_mul_f32_e32 v117, 0x4b800000, v116
	v_cmp_gt_f32_e32 vcc, s91, v116
	v_cvt_pk_bf16_f32 v115, v120, v121
	s_nop 1
	v_cndmask_b32_e32 v116, v116, v117, vcc
	v_rsq_f32_e32 v118, v116
	v_cvt_pk_bf16_f32 v116, v194, v195
	v_cvt_pk_bf16_f32 v117, v192, v193
	v_mov_b32_dpp v212, v200 quad_perm:[1,0,3,2] row_mask:0xf bank_mask:0xf
	v_mov_b32_dpp v213, v201 quad_perm:[1,0,3,2] row_mask:0xf bank_mask:0xf
	v_mov_b32_dpp v214, v202 quad_perm:[1,0,3,2] row_mask:0xf bank_mask:0xf
	v_mov_b32_dpp v215, v203 quad_perm:[1,0,3,2] row_mask:0xf bank_mask:0xf
	v_mov_b32_dpp v204, v114 quad_perm:[1,0,3,2] row_mask:0xf bank_mask:0xf
	v_mov_b32_dpp v205, v115 quad_perm:[1,0,3,2] row_mask:0xf bank_mask:0xf
	v_mov_b32_dpp v206, v116 quad_perm:[1,0,3,2] row_mask:0xf bank_mask:0xf
	v_mov_b32_dpp v207, v117 quad_perm:[1,0,3,2] row_mask:0xf bank_mask:0xf
	v_cndmask_b32_e64 v212, v114, v212, s[4:5]
	v_cndmask_b32_e64 v213, v115, v213, s[4:5]
	v_cndmask_b32_e64 v214, v116, v214, s[4:5]
	v_cndmask_b32_e64 v215, v117, v215, s[4:5]
	v_cndmask_b32_e64 v208, v204, v200, s[4:5]
	v_cndmask_b32_e64 v209, v205, v201, s[4:5]
	v_cndmask_b32_e64 v210, v206, v202, s[4:5]
	v_cndmask_b32_e64 v211, v207, v203, s[4:5]
	global_store_dwordx4 v[216:217], v[208:211], off nt
	global_store_dwordx4 v[216:217], v[212:215], off offset:1024 nt
	s_nop 1
; __device__ __forceinline__ unsigned cvt_pk_bf16(float lo, float hi) { unsigned r; asm volatile("v_cvt_pk_bf16_f32 %0, %1, %2" : "=v"(r) : "v"(lo), "v"(hi)); return r; }
;     __device__ __forceinline__ void operator()(const f32x4 (&acc)[2][2][4][2], const pg8::Unit& u, int wr, int wc, int fr, int fq) const {
;     ...
;                 for (int m = 0; m < 4; ++m) {
;                     float ss = 0.f;
; #pragma unroll
;                     for (int bj = 0; bj < 2; ++bj)
; #pragma unroll
;                         for (int n = 0; n < 2; ++n) { const f32x4 x = acc[ai][bj][m][n]; ss += (x[0] * x[0] + x[1] * x[1]) + (x[2] * x[2] + x[3] * x[3]); }
;                     ss = row4_sum(ss);
;                     const float r = rsqrtf(ss * (1.f / 64.f) + EPS) * osc;
;                     bf16_t* rowp = base + (size_t)(row0 + ai * 128 + m * 16) * 512 + col0;
; #pragma unroll
;                     for (int bj = 0; bj < 2; ++bj) { const f32x4 v0 = acc[ai][bj][m][0] * r * g[bj][0], v1 = acc[ai][bj][m][1] * r * g[bj][1];
;                         u32x4 w; w.x = cvt_pk_bf16(v0[0], v0[1]); w.y = cvt_pk_bf16(v0[2], v0[3]); w.z = cvt_pk_bf16(v1[0], v1[1]); w.w = cvt_pk_bf16(v1[2], v1[3]);
;                         *(u32x4*)(rowp + 32 * bj) = w; }
;                 }
	v_mul_f32_e32 v114, 0x45800000, v118
	v_cndmask_b32_e32 v114, v118, v114, vcc
	v_or_b32_e32 v116, 16, v172
	v_mul_f32_e32 v114, v178, v114
	v_ashrrev_i32_e32 v117, 31, v116
	v_lshlrev_b64 v[116:117], 10, v[116:117]
	v_pk_mul_f32 v[110:111], v[110:111], v[114:115] op_sel_hi:[1,0]
	v_pk_mul_f32 v[112:113], v[112:113], v[114:115] op_sel_hi:[1,0]
	v_pk_mul_f32 v[106:107], v[106:107], v[114:115] op_sel_hi:[1,0]
	v_pk_mul_f32 v[108:109], v[108:109], v[114:115] op_sel_hi:[1,0]
	v_pk_mul_f32 v[102:103], v[102:103], v[114:115] op_sel_hi:[1,0]
	v_lshl_add_u64 v[116:117], v[176:177], 0, v[116:117]
	v_pk_mul_f32 v[112:113], v[144:145], v[112:113]
	v_pk_mul_f32 v[110:111], v[142:143], v[110:111]
	v_pk_mul_f32 v[118:119], v[140:141], v[108:109]
	v_pk_mul_f32 v[108:109], v[138:139], v[106:107]
	v_cvt_pk_bf16_f32 v106, v110, v111
	v_cvt_pk_bf16_f32 v107, v112, v113
	v_pk_mul_f32 v[102:103], v[134:135], v[102:103]
	v_pk_mul_f32 v[98:99], v[98:99], v[114:115] op_sel_hi:[1,0]
	v_pk_mul_f32 v[100:101], v[100:101], v[114:115] op_sel_hi:[1,0]
	v_cvt_pk_bf16_f32 v108, v108, v109
	v_cvt_pk_bf16_f32 v109, v118, v119
	v_mov_b32_e32 v200, v106
	v_mov_b32_e32 v201, v107
	v_mov_b32_e32 v202, v108
	v_mov_b32_e32 v203, v109
	v_lshl_add_u64 v[216:217], v[116:117], 0, v[218:219]
	v_pk_mul_f32 v[104:105], v[104:105], v[114:115] op_sel_hi:[1,0]
	s_nop 0
	v_pk_mul_f32 v[106:107], v[132:133], v[100:101]
	v_pk_mul_f32 v[100:101], v[130:131], v[98:99]
	v_cvt_pk_bf16_f32 v98, v102, v103
	v_mul_f32_e32 v102, v95, v95
	v_mul_f32_e32 v103, v97, v97
	v_pk_mul_f32 v[104:105], v[136:137], v[104:105]
	v_fmac_f32_e32 v102, v94, v94
	v_fmac_f32_e32 v103, v96, v96
	v_cvt_pk_bf16_f32 v99, v104, v105
	v_add_f32_e32 v102, v102, v103
	v_mul_f32_e32 v103, v91, v91
	v_mul_f32_e32 v104, v93, v93
	v_fmac_f32_e32 v103, v90, v90
	v_fmac_f32_e32 v104, v92, v92
	v_add_f32_e32 v103, v103, v104
	v_add_f32_e32 v102, v102, v103
	v_mul_f32_e32 v103, v87, v87
	v_mul_f32_e32 v104, v89, v89
	v_fmac_f32_e32 v103, v86, v86
	v_fmac_f32_e32 v104, v88, v88
	v_add_f32_e32 v103, v103, v104
	v_add_f32_e32 v102, v102, v103
	v_mul_f32_e32 v103, v83, v83
	v_mul_f32_e32 v104, v85, v85
	v_fmac_f32_e32 v103, v82, v82
	v_fmac_f32_e32 v104, v84, v84
	v_add_f32_e32 v103, v103, v104
	v_add_f32_e32 v102, v102, v103
	v_mov_b32_e32 v103, v102
	s_nop 1
	v_permlane16_swap_b32_e32 v102, v103
	v_add_f32_e32 v102, v102, v103
	v_mov_b32_e32 v103, v102
	s_nop 1
	v_permlane32_swap_b32_e32 v102, v103
	v_add_f32_e32 v102, v102, v103
	v_fmamk_f32 v102, v102, 0x3c800000, v188
	v_mul_f32_e32 v103, 0x4b800000, v102
	v_cmp_gt_f32_e32 vcc, s91, v102
	v_cvt_pk_bf16_f32 v100, v100, v101
	v_cvt_pk_bf16_f32 v101, v106, v107
	v_mov_b32_dpp v212, v200 quad_perm:[1,0,3,2] row_mask:0xf bank_mask:0xf
	v_mov_b32_dpp v213, v201 quad_perm:[1,0,3,2] row_mask:0xf bank_mask:0xf
	v_mov_b32_dpp v214, v202 quad_perm:[1,0,3,2] row_mask:0xf bank_mask:0xf
	v_mov_b32_dpp v215, v203 quad_perm:[1,0,3,2] row_mask:0xf bank_mask:0xf
	v_mov_b32_dpp v204, v98 quad_perm:[1,0,3,2] row_mask:0xf bank_mask:0xf
	v_mov_b32_dpp v205, v99 quad_perm:[1,0,3,2] row_mask:0xf bank_mask:0xf
	v_mov_b32_dpp v206, v100 quad_perm:[1,0,3,2] row_mask:0xf bank_mask:0xf
	v_mov_b32_dpp v207, v101 quad_perm:[1,0,3,2] row_mask:0xf bank_mask:0xf
	v_cndmask_b32_e64 v212, v98, v212, s[4:5]
	v_cndmask_b32_e64 v213, v99, v213, s[4:5]
	v_cndmask_b32_e64 v214, v100, v214, s[4:5]
	v_cndmask_b32_e64 v215, v101, v215, s[4:5]
	v_cndmask_b32_e64 v208, v204, v200, s[4:5]
	v_cndmask_b32_e64 v209, v205, v201, s[4:5]
	v_cndmask_b32_e64 v210, v206, v202, s[4:5]
	v_cndmask_b32_e64 v211, v207, v203, s[4:5]
	global_store_dwordx4 v[216:217], v[208:211], off nt
	global_store_dwordx4 v[216:217], v[212:215], off offset:1024 nt
	s_nop 0
	v_cndmask_b32_e32 v102, v102, v103, vcc
	v_rsq_f32_e32 v102, v102
	v_or_b32_e32 v100, 32, v172
	v_ashrrev_i32_e32 v101, 31, v100
	v_lshlrev_b64 v[100:101], 10, v[100:101]
	v_mul_f32_e32 v98, 0x45800000, v102
	v_cndmask_b32_e32 v98, v102, v98, vcc
	v_mul_f32_e32 v98, v178, v98
	v_pk_mul_f32 v[94:95], v[94:95], v[98:99] op_sel_hi:[1,0]
	v_pk_mul_f32 v[96:97], v[96:97], v[98:99] op_sel_hi:[1,0]
	v_pk_mul_f32 v[90:91], v[90:91], v[98:99] op_sel_hi:[1,0]
	v_pk_mul_f32 v[92:93], v[92:93], v[98:99] op_sel_hi:[1,0]
	v_pk_mul_f32 v[86:87], v[86:87], v[98:99] op_sel_hi:[1,0]
	v_lshl_add_u64 v[100:101], v[176:177], 0, v[100:101]
	v_pk_mul_f32 v[96:97], v[144:145], v[96:97]
	v_pk_mul_f32 v[94:95], v[142:143], v[94:95]
	v_pk_mul_f32 v[102:103], v[140:141], v[92:93]
	v_pk_mul_f32 v[92:93], v[138:139], v[90:91]
	v_cvt_pk_bf16_f32 v90, v94, v95
	v_cvt_pk_bf16_f32 v91, v96, v97
	v_pk_mul_f32 v[86:87], v[134:135], v[86:87]
	v_pk_mul_f32 v[82:83], v[82:83], v[98:99] op_sel_hi:[1,0]
	v_pk_mul_f32 v[84:85], v[84:85], v[98:99] op_sel_hi:[1,0]
	v_cvt_pk_bf16_f32 v92, v92, v93
	v_cvt_pk_bf16_f32 v93, v102, v103
	v_mov_b32_e32 v200, v90
	v_mov_b32_e32 v201, v91
	v_mov_b32_e32 v202, v92
	v_mov_b32_e32 v203, v93
	v_lshl_add_u64 v[216:217], v[100:101], 0, v[218:219]
	v_pk_mul_f32 v[88:89], v[88:89], v[98:99] op_sel_hi:[1,0]
	s_nop 0
	v_pk_mul_f32 v[90:91], v[132:133], v[84:85]
	v_pk_mul_f32 v[84:85], v[130:131], v[82:83]
	v_cvt_pk_bf16_f32 v82, v86, v87
	v_mul_f32_e32 v86, v79, v79
	v_mul_f32_e32 v87, v81, v81
	v_pk_mul_f32 v[88:89], v[136:137], v[88:89]
	v_fmac_f32_e32 v86, v78, v78
	v_fmac_f32_e32 v87, v80, v80
	v_cvt_pk_bf16_f32 v83, v88, v89
	v_add_f32_e32 v86, v86, v87
	v_mul_f32_e32 v87, v75, v75
	v_mul_f32_e32 v88, v77, v77
	v_fmac_f32_e32 v87, v74, v74
	v_fmac_f32_e32 v88, v76, v76
	v_add_f32_e32 v87, v87, v88
	v_add_f32_e32 v86, v86, v87
	v_mul_f32_e32 v87, v71, v71
	v_mul_f32_e32 v88, v73, v73
; __device__ __forceinline__ unsigned cvt_pk_bf16(float lo, float hi) { unsigned r; asm volatile("v_cvt_pk_bf16_f32 %0, %1, %2" : "=v"(r) : "v"(lo), "v"(hi)); return r; }
;     __device__ __forceinline__ void operator()(const f32x4 (&acc)[2][2][4][2], const pg8::Unit& u, int wr, int wc, int fr, int fq) const {
;     ...
;                 for (int m = 0; m < 4; ++m) {
;                     float ss = 0.f;
; #pragma unroll
;                     for (int bj = 0; bj < 2; ++bj)
; #pragma unroll
;                         for (int n = 0; n < 2; ++n) { const f32x4 x = acc[ai][bj][m][n]; ss += (x[0] * x[0] + x[1] * x[1]) + (x[2] * x[2] + x[3] * x[3]); }
;                     ss = row4_sum(ss);
;                     const float r = rsqrtf(ss * (1.f / 64.f) + EPS) * osc;
;                     bf16_t* rowp = base + (size_t)(row0 + ai * 128 + m * 16) * 512 + col0;
; #pragma unroll
;                     for (int bj = 0; bj < 2; ++bj) { const f32x4 v0 = acc[ai][bj][m][0] * r * g[bj][0], v1 = acc[ai][bj][m][1] * r * g[bj][1];
;                         u32x4 w; w.x = cvt_pk_bf16(v0[0], v0[1]); w.y = cvt_pk_bf16(v0[2], v0[3]); w.z = cvt_pk_bf16(v1[0], v1[1]); w.w = cvt_pk_bf16(v1[2], v1[3]);
;                         *(u32x4*)(rowp + 32 * bj) = w; }
;                 }
	v_fmac_f32_e32 v87, v70, v70
	v_fmac_f32_e32 v88, v72, v72
	v_add_f32_e32 v87, v87, v88
	v_add_f32_e32 v86, v86, v87
	v_mul_f32_e32 v87, v67, v67
	v_mul_f32_e32 v88, v69, v69
	v_fmac_f32_e32 v87, v66, v66
	v_fmac_f32_e32 v88, v68, v68
	v_add_f32_e32 v87, v87, v88
	v_add_f32_e32 v86, v86, v87
	v_mov_b32_e32 v87, v86
	s_nop 1
	v_permlane16_swap_b32_e32 v86, v87
	v_add_f32_e32 v86, v86, v87
	v_mov_b32_e32 v87, v86
	s_nop 1
	v_permlane32_swap_b32_e32 v86, v87
	v_add_f32_e32 v86, v86, v87
	v_fmamk_f32 v86, v86, 0x3c800000, v188
	v_mul_f32_e32 v87, 0x4b800000, v86
	v_cmp_gt_f32_e32 vcc, s91, v86
	v_cvt_pk_bf16_f32 v84, v84, v85
	v_cvt_pk_bf16_f32 v85, v90, v91
	v_mov_b32_dpp v212, v200 quad_perm:[1,0,3,2] row_mask:0xf bank_mask:0xf
	v_mov_b32_dpp v213, v201 quad_perm:[1,0,3,2] row_mask:0xf bank_mask:0xf
	v_mov_b32_dpp v214, v202 quad_perm:[1,0,3,2] row_mask:0xf bank_mask:0xf
	v_mov_b32_dpp v215, v203 quad_perm:[1,0,3,2] row_mask:0xf bank_mask:0xf
	v_mov_b32_dpp v204, v82 quad_perm:[1,0,3,2] row_mask:0xf bank_mask:0xf
	v_mov_b32_dpp v205, v83 quad_perm:[1,0,3,2] row_mask:0xf bank_mask:0xf
	v_mov_b32_dpp v206, v84 quad_perm:[1,0,3,2] row_mask:0xf bank_mask:0xf
	v_mov_b32_dpp v207, v85 quad_perm:[1,0,3,2] row_mask:0xf bank_mask:0xf
	v_cndmask_b32_e64 v212, v82, v212, s[4:5]
	v_cndmask_b32_e64 v213, v83, v213, s[4:5]
	v_cndmask_b32_e64 v214, v84, v214, s[4:5]
	v_cndmask_b32_e64 v215, v85, v215, s[4:5]
	v_cndmask_b32_e64 v208, v204, v200, s[4:5]
	v_cndmask_b32_e64 v209, v205, v201, s[4:5]
	v_cndmask_b32_e64 v210, v206, v202, s[4:5]
	v_cndmask_b32_e64 v211, v207, v203, s[4:5]
	global_store_dwordx4 v[216:217], v[208:211], off nt
	global_store_dwordx4 v[216:217], v[212:215], off offset:1024 nt
	s_nop 0
	v_cndmask_b32_e32 v86, v86, v87, vcc
	v_rsq_f32_e32 v86, v86
	v_or_b32_e32 v84, 48, v172
	v_ashrrev_i32_e32 v85, 31, v84
	v_lshlrev_b64 v[84:85], 10, v[84:85]
	v_mul_f32_e32 v82, 0x45800000, v86
	v_cndmask_b32_e32 v82, v86, v82, vcc
	v_mul_f32_e32 v82, v178, v82
	v_pk_mul_f32 v[78:79], v[78:79], v[82:83] op_sel_hi:[1,0]
	v_pk_mul_f32 v[80:81], v[80:81], v[82:83] op_sel_hi:[1,0]
	v_pk_mul_f32 v[74:75], v[74:75], v[82:83] op_sel_hi:[1,0]
	v_pk_mul_f32 v[76:77], v[76:77], v[82:83] op_sel_hi:[1,0]
	v_pk_mul_f32 v[70:71], v[70:71], v[82:83] op_sel_hi:[1,0]
	v_lshl_add_u64 v[84:85], v[176:177], 0, v[84:85]
	v_pk_mul_f32 v[80:81], v[144:145], v[80:81]
	v_pk_mul_f32 v[78:79], v[142:143], v[78:79]
	v_pk_mul_f32 v[86:87], v[140:141], v[76:77]
	v_pk_mul_f32 v[76:77], v[138:139], v[74:75]
	v_cvt_pk_bf16_f32 v74, v78, v79
	v_cvt_pk_bf16_f32 v75, v80, v81
	v_pk_mul_f32 v[70:71], v[134:135], v[70:71]
	v_pk_mul_f32 v[66:67], v[66:67], v[82:83] op_sel_hi:[1,0]
	v_pk_mul_f32 v[68:69], v[68:69], v[82:83] op_sel_hi:[1,0]
	v_cvt_pk_bf16_f32 v76, v76, v77
	v_cvt_pk_bf16_f32 v77, v86, v87
	v_mov_b32_e32 v200, v74
	v_mov_b32_e32 v201, v75
	v_mov_b32_e32 v202, v76
	v_mov_b32_e32 v203, v77
	v_lshl_add_u64 v[216:217], v[84:85], 0, v[218:219]
	v_pk_mul_f32 v[72:73], v[72:73], v[82:83] op_sel_hi:[1,0]
	s_nop 0
	v_pk_mul_f32 v[74:75], v[132:133], v[68:69]
	v_pk_mul_f32 v[68:69], v[130:131], v[66:67]
	v_cvt_pk_bf16_f32 v66, v70, v71
	v_mul_f32_e32 v70, v63, v63
	v_mul_f32_e32 v71, v65, v65
	v_pk_mul_f32 v[72:73], v[136:137], v[72:73]
	v_fmac_f32_e32 v70, v62, v62
	v_fmac_f32_e32 v71, v64, v64
	v_cvt_pk_bf16_f32 v67, v72, v73
	v_add_f32_e32 v70, v70, v71
	v_mul_f32_e32 v71, v59, v59
	v_mul_f32_e32 v72, v61, v61
	v_fmac_f32_e32 v71, v58, v58
	v_fmac_f32_e32 v72, v60, v60
	v_add_f32_e32 v71, v71, v72
	v_add_f32_e32 v70, v70, v71
	v_mul_f32_e32 v71, v55, v55
	v_mul_f32_e32 v72, v57, v57
	v_fmac_f32_e32 v71, v54, v54
	v_fmac_f32_e32 v72, v56, v56
	v_add_f32_e32 v71, v71, v72
	v_add_f32_e32 v70, v70, v71
	v_mul_f32_e32 v71, v51, v51
	v_mul_f32_e32 v72, v53, v53
	v_fmac_f32_e32 v71, v50, v50
	v_fmac_f32_e32 v72, v52, v52
	v_add_f32_e32 v71, v71, v72
	v_add_f32_e32 v70, v70, v71
	v_mov_b32_e32 v71, v70
	s_nop 1
	v_permlane16_swap_b32_e32 v70, v71
	v_add_f32_e32 v70, v70, v71
	v_mov_b32_e32 v71, v70
	s_nop 1
	v_permlane32_swap_b32_e32 v70, v71
	v_add_f32_e32 v70, v70, v71
	v_fmamk_f32 v70, v70, 0x3c800000, v188
	v_mul_f32_e32 v71, 0x4b800000, v70
	v_cmp_gt_f32_e32 vcc, s91, v70
	v_cvt_pk_bf16_f32 v68, v68, v69
	v_cvt_pk_bf16_f32 v69, v74, v75
	v_mov_b32_dpp v212, v200 quad_perm:[1,0,3,2] row_mask:0xf bank_mask:0xf
	v_mov_b32_dpp v213, v201 quad_perm:[1,0,3,2] row_mask:0xf bank_mask:0xf
	v_mov_b32_dpp v214, v202 quad_perm:[1,0,3,2] row_mask:0xf bank_mask:0xf
	v_mov_b32_dpp v215, v203 quad_perm:[1,0,3,2] row_mask:0xf bank_mask:0xf
	v_mov_b32_dpp v204, v66 quad_perm:[1,0,3,2] row_mask:0xf bank_mask:0xf
	v_mov_b32_dpp v205, v67 quad_perm:[1,0,3,2] row_mask:0xf bank_mask:0xf
	v_mov_b32_dpp v206, v68 quad_perm:[1,0,3,2] row_mask:0xf bank_mask:0xf
	v_mov_b32_dpp v207, v69 quad_perm:[1,0,3,2] row_mask:0xf bank_mask:0xf
	v_cndmask_b32_e64 v212, v66, v212, s[4:5]
	v_cndmask_b32_e64 v213, v67, v213, s[4:5]
	v_cndmask_b32_e64 v214, v68, v214, s[4:5]
	v_cndmask_b32_e64 v215, v69, v215, s[4:5]
	v_cndmask_b32_e64 v208, v204, v200, s[4:5]
	v_cndmask_b32_e64 v209, v205, v201, s[4:5]
	v_cndmask_b32_e64 v210, v206, v202, s[4:5]
	v_cndmask_b32_e64 v211, v207, v203, s[4:5]
	global_store_dwordx4 v[216:217], v[208:211], off nt
	global_store_dwordx4 v[216:217], v[212:215], off offset:1024 nt
	s_nop 0
	v_cndmask_b32_e32 v70, v70, v71, vcc
	v_rsq_f32_e32 v70, v70
	v_lshl_add_u64 v[68:69], v[174:175], 0, s[16:17]
	v_mul_f32_e32 v66, 0x45800000, v70
	v_cndmask_b32_e32 v66, v70, v66, vcc
	v_mul_f32_e32 v66, v178, v66
	v_pk_mul_f32 v[62:63], v[62:63], v[66:67] op_sel_hi:[1,0]
	v_pk_mul_f32 v[58:59], v[58:59], v[66:67] op_sel_hi:[1,0]
; __device__ __forceinline__ unsigned cvt_pk_bf16(float lo, float hi) { unsigned r; asm volatile("v_cvt_pk_bf16_f32 %0, %1, %2" : "=v"(r) : "v"(lo), "v"(hi)); return r; }
;     __device__ __forceinline__ void operator()(const f32x4 (&acc)[2][2][4][2], const pg8::Unit& u, int wr, int wc, int fr, int fq) const {
;     ...
;                 for (int m = 0; m < 4; ++m) {
;                     float ss = 0.f;
; #pragma unroll
;                     for (int bj = 0; bj < 2; ++bj)
; #pragma unroll
;                         for (int n = 0; n < 2; ++n) { const f32x4 x = acc[ai][bj][m][n]; ss += (x[0] * x[0] + x[1] * x[1]) + (x[2] * x[2] + x[3] * x[3]); }
;                     ss = row4_sum(ss);
;                     const float r = rsqrtf(ss * (1.f / 64.f) + EPS) * osc;
;                     bf16_t* rowp = base + (size_t)(row0 + ai * 128 + m * 16) * 512 + col0;
; #pragma unroll
;                     for (int bj = 0; bj < 2; ++bj) { const f32x4 v0 = acc[ai][bj][m][0] * r * g[bj][0], v1 = acc[ai][bj][m][1] * r * g[bj][1];
;                         u32x4 w; w.x = cvt_pk_bf16(v0[0], v0[1]); w.y = cvt_pk_bf16(v0[2], v0[3]); w.z = cvt_pk_bf16(v1[0], v1[1]); w.w = cvt_pk_bf16(v1[2], v1[3]);
;                         *(u32x4*)(rowp + 32 * bj) = w; }
;                 }
	v_pk_mul_f32 v[62:63], v[142:143], v[62:63]
	v_pk_mul_f32 v[60:61], v[60:61], v[66:67] op_sel_hi:[1,0]
	v_pk_mul_f32 v[64:65], v[64:65], v[66:67] op_sel_hi:[1,0]
	v_pk_mul_f32 v[70:71], v[140:141], v[60:61]
	v_pk_mul_f32 v[60:61], v[138:139], v[58:59]
	v_cvt_pk_bf16_f32 v58, v62, v63
	v_add_co_u32_e32 v62, vcc, s87, v174
	v_pk_mul_f32 v[54:55], v[54:55], v[66:67] op_sel_hi:[1,0]
	v_pk_mul_f32 v[64:65], v[144:145], v[64:65]
	v_addc_co_u32_e32 v63, vcc, 0, v175, vcc
	v_cvt_pk_bf16_f32 v59, v64, v65
	v_pk_mul_f32 v[54:55], v[134:135], v[54:55]
	v_pk_mul_f32 v[50:51], v[50:51], v[66:67] op_sel_hi:[1,0]
	v_pk_mul_f32 v[52:53], v[52:53], v[66:67] op_sel_hi:[1,0]
	v_cvt_pk_bf16_f32 v60, v60, v61
	v_cvt_pk_bf16_f32 v61, v70, v71
	v_mov_b32_e32 v200, v58
	v_mov_b32_e32 v201, v59
	v_mov_b32_e32 v202, v60
	v_mov_b32_e32 v203, v61
	v_lshl_add_u64 v[216:217], v[62:63], 0, v[218:219]
	v_pk_mul_f32 v[56:57], v[56:57], v[66:67] op_sel_hi:[1,0]
	s_nop 0
	v_pk_mul_f32 v[58:59], v[132:133], v[52:53]
	v_pk_mul_f32 v[52:53], v[130:131], v[50:51]
	v_cvt_pk_bf16_f32 v50, v54, v55
	v_mul_f32_e32 v54, v47, v47
	v_mul_f32_e32 v55, v49, v49
	v_pk_mul_f32 v[56:57], v[136:137], v[56:57]
	v_fmac_f32_e32 v54, v46, v46
	v_fmac_f32_e32 v55, v48, v48
	v_cvt_pk_bf16_f32 v51, v56, v57
	v_add_f32_e32 v54, v54, v55
	v_mul_f32_e32 v55, v43, v43
	v_mul_f32_e32 v56, v45, v45
	v_fmac_f32_e32 v55, v42, v42
	v_fmac_f32_e32 v56, v44, v44
	v_add_f32_e32 v55, v55, v56
	v_add_f32_e32 v54, v54, v55
	v_mul_f32_e32 v55, v39, v39
	v_mul_f32_e32 v56, v41, v41
	v_fmac_f32_e32 v55, v38, v38
	v_fmac_f32_e32 v56, v40, v40
	v_add_f32_e32 v55, v55, v56
	v_add_f32_e32 v54, v54, v55
	v_mul_f32_e32 v55, v35, v35
	v_mul_f32_e32 v56, v37, v37
	v_fmac_f32_e32 v55, v34, v34
	v_fmac_f32_e32 v56, v36, v36
	v_add_f32_e32 v55, v55, v56
	v_add_f32_e32 v54, v54, v55
	v_mov_b32_e32 v55, v54
	s_nop 1
	v_permlane16_swap_b32_e32 v54, v55
	v_add_f32_e32 v54, v54, v55
	v_mov_b32_e32 v55, v54
	s_nop 1
	v_permlane32_swap_b32_e32 v54, v55
	v_add_f32_e32 v54, v54, v55
	v_fmamk_f32 v54, v54, 0x3c800000, v188
	v_mul_f32_e32 v55, 0x4b800000, v54
	v_cmp_gt_f32_e32 vcc, s91, v54
	v_cvt_pk_bf16_f32 v52, v52, v53
	v_cvt_pk_bf16_f32 v53, v58, v59
	v_mov_b32_dpp v212, v200 quad_perm:[1,0,3,2] row_mask:0xf bank_mask:0xf
	v_mov_b32_dpp v213, v201 quad_perm:[1,0,3,2] row_mask:0xf bank_mask:0xf
	v_mov_b32_dpp v214, v202 quad_perm:[1,0,3,2] row_mask:0xf bank_mask:0xf
	v_mov_b32_dpp v215, v203 quad_perm:[1,0,3,2] row_mask:0xf bank_mask:0xf
	v_mov_b32_dpp v204, v50 quad_perm:[1,0,3,2] row_mask:0xf bank_mask:0xf
	v_mov_b32_dpp v205, v51 quad_perm:[1,0,3,2] row_mask:0xf bank_mask:0xf
	v_mov_b32_dpp v206, v52 quad_perm:[1,0,3,2] row_mask:0xf bank_mask:0xf
	v_mov_b32_dpp v207, v53 quad_perm:[1,0,3,2] row_mask:0xf bank_mask:0xf
	v_cndmask_b32_e64 v212, v50, v212, s[4:5]
	v_cndmask_b32_e64 v213, v51, v213, s[4:5]
	v_cndmask_b32_e64 v214, v52, v214, s[4:5]
	v_cndmask_b32_e64 v215, v53, v215, s[4:5]
	v_cndmask_b32_e64 v208, v204, v200, s[4:5]
	v_cndmask_b32_e64 v209, v205, v201, s[4:5]
	v_cndmask_b32_e64 v210, v206, v202, s[4:5]
	v_cndmask_b32_e64 v211, v207, v203, s[4:5]
	global_store_dwordx4 v[216:217], v[208:211], off nt
	global_store_dwordx4 v[216:217], v[212:215], off offset:1024 nt
	s_nop 0
	v_cndmask_b32_e32 v54, v54, v55, vcc
	v_rsq_f32_e32 v54, v54
	v_lshl_add_u64 v[52:53], v[174:175], 0, s[18:19]
	v_mul_f32_e32 v50, 0x45800000, v54
	v_cndmask_b32_e32 v50, v54, v50, vcc
	v_mul_f32_e32 v50, v178, v50
	v_pk_mul_f32 v[46:47], v[46:47], v[50:51] op_sel_hi:[1,0]
	v_pk_mul_f32 v[42:43], v[42:43], v[50:51] op_sel_hi:[1,0]
	v_pk_mul_f32 v[46:47], v[142:143], v[46:47]
	v_pk_mul_f32 v[44:45], v[44:45], v[50:51] op_sel_hi:[1,0]
	v_pk_mul_f32 v[48:49], v[48:49], v[50:51] op_sel_hi:[1,0]
	v_pk_mul_f32 v[54:55], v[140:141], v[44:45]
	v_pk_mul_f32 v[44:45], v[138:139], v[42:43]
	v_cvt_pk_bf16_f32 v42, v46, v47
	v_add_co_u32_e32 v46, vcc, s88, v174
	v_pk_mul_f32 v[38:39], v[38:39], v[50:51] op_sel_hi:[1,0]
	v_pk_mul_f32 v[48:49], v[144:145], v[48:49]
	v_addc_co_u32_e32 v47, vcc, 0, v175, vcc
	v_cvt_pk_bf16_f32 v43, v48, v49
	v_pk_mul_f32 v[38:39], v[134:135], v[38:39]
	v_pk_mul_f32 v[34:35], v[34:35], v[50:51] op_sel_hi:[1,0]
	v_pk_mul_f32 v[36:37], v[36:37], v[50:51] op_sel_hi:[1,0]
	v_cvt_pk_bf16_f32 v44, v44, v45
	v_cvt_pk_bf16_f32 v45, v54, v55
	v_mov_b32_e32 v200, v42
	v_mov_b32_e32 v201, v43
	v_mov_b32_e32 v202, v44
	v_mov_b32_e32 v203, v45
	v_lshl_add_u64 v[216:217], v[46:47], 0, v[218:219]
	v_pk_mul_f32 v[40:41], v[40:41], v[50:51] op_sel_hi:[1,0]
	s_nop 0
	v_pk_mul_f32 v[42:43], v[132:133], v[36:37]
	v_pk_mul_f32 v[36:37], v[130:131], v[34:35]
	v_cvt_pk_bf16_f32 v34, v38, v39
	v_mul_f32_e32 v38, v31, v31
	v_mul_f32_e32 v39, v33, v33
	v_pk_mul_f32 v[40:41], v[136:137], v[40:41]
	v_fmac_f32_e32 v38, v30, v30
	v_fmac_f32_e32 v39, v32, v32
	v_cvt_pk_bf16_f32 v35, v40, v41
	v_add_f32_e32 v38, v38, v39
	v_mul_f32_e32 v39, v27, v27
	v_mul_f32_e32 v40, v29, v29
	v_fmac_f32_e32 v39, v26, v26
	v_fmac_f32_e32 v40, v28, v28
	v_add_f32_e32 v39, v39, v40
	v_add_f32_e32 v38, v38, v39
	v_mul_f32_e32 v39, v23, v23
	v_mul_f32_e32 v40, v25, v25
	v_fmac_f32_e32 v39, v22, v22
	v_fmac_f32_e32 v40, v24, v24
	v_add_f32_e32 v39, v39, v40
	v_add_f32_e32 v38, v38, v39
	v_mul_f32_e32 v39, v19, v19
	v_mul_f32_e32 v40, v21, v21
	v_fmac_f32_e32 v39, v18, v18
	v_fmac_f32_e32 v40, v20, v20
	v_add_f32_e32 v39, v39, v40
	v_add_f32_e32 v38, v38, v39
	v_mov_b32_e32 v39, v38
	s_nop 1
	v_permlane16_swap_b32_e32 v38, v39
	v_add_f32_e32 v38, v38, v39
	v_mov_b32_e32 v39, v38
	s_nop 1
	v_permlane32_swap_b32_e32 v38, v39
	v_add_f32_e32 v38, v38, v39
	v_fmamk_f32 v38, v38, 0x3c800000, v188
; __device__ __forceinline__ unsigned cvt_pk_bf16(float lo, float hi) { unsigned r; asm volatile("v_cvt_pk_bf16_f32 %0, %1, %2" : "=v"(r) : "v"(lo), "v"(hi)); return r; }
;     __device__ __forceinline__ void operator()(const f32x4 (&acc)[2][2][4][2], const pg8::Unit& u, int wr, int wc, int fr, int fq) const {
;     ...
;                 for (int m = 0; m < 4; ++m) {
;                     float ss = 0.f;
; #pragma unroll
;                     for (int bj = 0; bj < 2; ++bj)
; #pragma unroll
;                         for (int n = 0; n < 2; ++n) { const f32x4 x = acc[ai][bj][m][n]; ss += (x[0] * x[0] + x[1] * x[1]) + (x[2] * x[2] + x[3] * x[3]); }
;                     ss = row4_sum(ss);
;                     const float r = rsqrtf(ss * (1.f / 64.f) + EPS) * osc;
;                     bf16_t* rowp = base + (size_t)(row0 + ai * 128 + m * 16) * 512 + col0;
; #pragma unroll
;                     for (int bj = 0; bj < 2; ++bj) { const f32x4 v0 = acc[ai][bj][m][0] * r * g[bj][0], v1 = acc[ai][bj][m][1] * r * g[bj][1];
;                         u32x4 w; w.x = cvt_pk_bf16(v0[0], v0[1]); w.y = cvt_pk_bf16(v0[2], v0[3]); w.z = cvt_pk_bf16(v1[0], v1[1]); w.w = cvt_pk_bf16(v1[2], v1[3]);
;                         *(u32x4*)(rowp + 32 * bj) = w; }
;                 }
	v_mul_f32_e32 v39, 0x4b800000, v38
	v_cmp_gt_f32_e32 vcc, s91, v38
	v_cvt_pk_bf16_f32 v36, v36, v37
	v_cvt_pk_bf16_f32 v37, v42, v43
	v_mov_b32_dpp v212, v200 quad_perm:[1,0,3,2] row_mask:0xf bank_mask:0xf
	v_mov_b32_dpp v213, v201 quad_perm:[1,0,3,2] row_mask:0xf bank_mask:0xf
	v_mov_b32_dpp v214, v202 quad_perm:[1,0,3,2] row_mask:0xf bank_mask:0xf
	v_mov_b32_dpp v215, v203 quad_perm:[1,0,3,2] row_mask:0xf bank_mask:0xf
	v_mov_b32_dpp v204, v34 quad_perm:[1,0,3,2] row_mask:0xf bank_mask:0xf
	v_mov_b32_dpp v205, v35 quad_perm:[1,0,3,2] row_mask:0xf bank_mask:0xf
	v_mov_b32_dpp v206, v36 quad_perm:[1,0,3,2] row_mask:0xf bank_mask:0xf
	v_mov_b32_dpp v207, v37 quad_perm:[1,0,3,2] row_mask:0xf bank_mask:0xf
	v_cndmask_b32_e64 v212, v34, v212, s[4:5]
	v_cndmask_b32_e64 v213, v35, v213, s[4:5]
	v_cndmask_b32_e64 v214, v36, v214, s[4:5]
	v_cndmask_b32_e64 v215, v37, v215, s[4:5]
	v_cndmask_b32_e64 v208, v204, v200, s[4:5]
	v_cndmask_b32_e64 v209, v205, v201, s[4:5]
	v_cndmask_b32_e64 v210, v206, v202, s[4:5]
	v_cndmask_b32_e64 v211, v207, v203, s[4:5]
	global_store_dwordx4 v[216:217], v[208:211], off nt
	global_store_dwordx4 v[216:217], v[212:215], off offset:1024 nt
	s_nop 0
	v_cndmask_b32_e32 v38, v38, v39, vcc
	v_rsq_f32_e32 v38, v38
	v_lshl_add_u64 v[36:37], v[174:175], 0, s[20:21]
	v_mul_f32_e32 v34, 0x45800000, v38
	v_cndmask_b32_e32 v34, v38, v34, vcc
	v_mul_f32_e32 v34, v178, v34
	v_pk_mul_f32 v[30:31], v[30:31], v[34:35] op_sel_hi:[1,0]
	v_pk_mul_f32 v[26:27], v[26:27], v[34:35] op_sel_hi:[1,0]
	v_pk_mul_f32 v[30:31], v[142:143], v[30:31]
	v_pk_mul_f32 v[28:29], v[28:29], v[34:35] op_sel_hi:[1,0]
	v_pk_mul_f32 v[32:33], v[32:33], v[34:35] op_sel_hi:[1,0]
	v_pk_mul_f32 v[38:39], v[140:141], v[28:29]
	v_pk_mul_f32 v[28:29], v[138:139], v[26:27]
	v_cvt_pk_bf16_f32 v26, v30, v31
	v_add_co_u32_e32 v30, vcc, s89, v174
	v_pk_mul_f32 v[22:23], v[22:23], v[34:35] op_sel_hi:[1,0]
	v_pk_mul_f32 v[32:33], v[144:145], v[32:33]
	v_addc_co_u32_e32 v31, vcc, 0, v175, vcc
	v_cvt_pk_bf16_f32 v27, v32, v33
	v_pk_mul_f32 v[22:23], v[134:135], v[22:23]
	v_pk_mul_f32 v[18:19], v[18:19], v[34:35] op_sel_hi:[1,0]
	v_pk_mul_f32 v[20:21], v[20:21], v[34:35] op_sel_hi:[1,0]
	v_cvt_pk_bf16_f32 v28, v28, v29
	v_cvt_pk_bf16_f32 v29, v38, v39
	v_mov_b32_e32 v200, v26
	v_mov_b32_e32 v201, v27
	v_mov_b32_e32 v202, v28
	v_mov_b32_e32 v203, v29
	v_lshl_add_u64 v[216:217], v[30:31], 0, v[218:219]
	v_pk_mul_f32 v[24:25], v[24:25], v[34:35] op_sel_hi:[1,0]
	s_nop 0
	v_pk_mul_f32 v[26:27], v[132:133], v[20:21]
	v_pk_mul_f32 v[20:21], v[130:131], v[18:19]
	v_cvt_pk_bf16_f32 v18, v22, v23
	v_mul_f32_e32 v22, v15, v15
	v_mul_f32_e32 v23, v17, v17
	v_pk_mul_f32 v[24:25], v[136:137], v[24:25]
	v_fmac_f32_e32 v22, v14, v14
	v_fmac_f32_e32 v23, v16, v16
	v_cvt_pk_bf16_f32 v19, v24, v25
	v_add_f32_e32 v22, v22, v23
	v_mul_f32_e32 v23, v11, v11
	v_mul_f32_e32 v24, v13, v13
	v_fmac_f32_e32 v23, v10, v10
	v_fmac_f32_e32 v24, v12, v12
	v_add_f32_e32 v23, v23, v24
	v_add_f32_e32 v22, v22, v23
	v_mul_f32_e32 v23, v7, v7
	v_mul_f32_e32 v24, v9, v9
	v_fmac_f32_e32 v23, v6, v6
	v_fmac_f32_e32 v24, v8, v8
	v_add_f32_e32 v23, v23, v24
	v_add_f32_e32 v22, v22, v23
	v_mul_f32_e32 v23, v3, v3
	v_mul_f32_e32 v24, v5, v5
	v_fmac_f32_e32 v23, v2, v2
	v_fmac_f32_e32 v24, v4, v4
	v_add_f32_e32 v23, v23, v24
	v_add_f32_e32 v22, v22, v23
	v_mov_b32_e32 v23, v22
	s_nop 1
	v_permlane16_swap_b32_e32 v22, v23
	v_add_f32_e32 v22, v22, v23
	v_mov_b32_e32 v23, v22
	s_nop 1
	v_permlane32_swap_b32_e32 v22, v23
	v_add_f32_e32 v22, v22, v23
	v_fmamk_f32 v22, v22, 0x3c800000, v188
	v_mul_f32_e32 v23, 0x4b800000, v22
	v_cmp_gt_f32_e32 vcc, s91, v22
	v_cvt_pk_bf16_f32 v20, v20, v21
	v_cvt_pk_bf16_f32 v21, v26, v27
; __device__ __forceinline__ unsigned cvt_pk_bf16(float lo, float hi) { unsigned r; asm volatile("v_cvt_pk_bf16_f32 %0, %1, %2" : "=v"(r) : "v"(lo), "v"(hi)); return r; }
;     __device__ __forceinline__ void operator()(const f32x4 (&acc)[2][2][4][2], const pg8::Unit& u, int wr, int wc, int fr, int fq) const {
;     ...
;                 for (int m = 0; m < 4; ++m) {
;                     float ss = 0.f;
; #pragma unroll
;                     for (int bj = 0; bj < 2; ++bj)
; #pragma unroll
;                         for (int n = 0; n < 2; ++n) { const f32x4 x = acc[ai][bj][m][n]; ss += (x[0] * x[0] + x[1] * x[1]) + (x[2] * x[2] + x[3] * x[3]); }
;                     ss = row4_sum(ss);
;                     const float r = rsqrtf(ss * (1.f / 64.f) + EPS) * osc;
;                     bf16_t* rowp = base + (size_t)(row0 + ai * 128 + m * 16) * 512 + col0;
; #pragma unroll
;                     for (int bj = 0; bj < 2; ++bj) { const f32x4 v0 = acc[ai][bj][m][0] * r * g[bj][0], v1 = acc[ai][bj][m][1] * r * g[bj][1];
;                         u32x4 w; w.x = cvt_pk_bf16(v0[0], v0[1]); w.y = cvt_pk_bf16(v0[2], v0[3]); w.z = cvt_pk_bf16(v1[0], v1[1]); w.w = cvt_pk_bf16(v1[2], v1[3]);
;                         *(u32x4*)(rowp + 32 * bj) = w; }
;                 }
	v_mov_b32_dpp v212, v200 quad_perm:[1,0,3,2] row_mask:0xf bank_mask:0xf
	v_mov_b32_dpp v213, v201 quad_perm:[1,0,3,2] row_mask:0xf bank_mask:0xf
	v_mov_b32_dpp v214, v202 quad_perm:[1,0,3,2] row_mask:0xf bank_mask:0xf
	v_mov_b32_dpp v215, v203 quad_perm:[1,0,3,2] row_mask:0xf bank_mask:0xf
	v_mov_b32_dpp v204, v18 quad_perm:[1,0,3,2] row_mask:0xf bank_mask:0xf
	v_mov_b32_dpp v205, v19 quad_perm:[1,0,3,2] row_mask:0xf bank_mask:0xf
	v_mov_b32_dpp v206, v20 quad_perm:[1,0,3,2] row_mask:0xf bank_mask:0xf
	v_mov_b32_dpp v207, v21 quad_perm:[1,0,3,2] row_mask:0xf bank_mask:0xf
	v_cndmask_b32_e64 v212, v18, v212, s[4:5]
	v_cndmask_b32_e64 v213, v19, v213, s[4:5]
	v_cndmask_b32_e64 v214, v20, v214, s[4:5]
	v_cndmask_b32_e64 v215, v21, v215, s[4:5]
	v_cndmask_b32_e64 v208, v204, v200, s[4:5]
	v_cndmask_b32_e64 v209, v205, v201, s[4:5]
	v_cndmask_b32_e64 v210, v206, v202, s[4:5]
	v_cndmask_b32_e64 v211, v207, v203, s[4:5]
	global_store_dwordx4 v[216:217], v[208:211], off nt
	global_store_dwordx4 v[216:217], v[212:215], off offset:1024 nt
	s_nop 0
	v_cndmask_b32_e32 v22, v22, v23, vcc
	v_rsq_f32_e32 v22, v22
	v_lshl_add_u64 v[20:21], v[174:175], 0, s[24:25]
	v_mul_f32_e32 v18, 0x45800000, v22
	v_cndmask_b32_e32 v18, v22, v18, vcc
	v_mul_f32_e32 v18, v178, v18
	v_pk_mul_f32 v[14:15], v[14:15], v[18:19] op_sel_hi:[1,0]
	v_pk_mul_f32 v[10:11], v[10:11], v[18:19] op_sel_hi:[1,0]
	v_pk_mul_f32 v[14:15], v[142:143], v[14:15]
	v_pk_mul_f32 v[12:13], v[12:13], v[18:19] op_sel_hi:[1,0]
	v_pk_mul_f32 v[16:17], v[16:17], v[18:19] op_sel_hi:[1,0]
	v_pk_mul_f32 v[22:23], v[140:141], v[12:13]
	v_pk_mul_f32 v[12:13], v[138:139], v[10:11]
	v_cvt_pk_bf16_f32 v10, v14, v15
	v_add_co_u32_e32 v14, vcc, s90, v174
	v_pk_mul_f32 v[16:17], v[144:145], v[16:17]
	s_nop 0
	v_addc_co_u32_e32 v15, vcc, 0, v175, vcc
	v_cvt_pk_bf16_f32 v11, v16, v17
	v_pk_mul_f32 v[2:3], v[2:3], v[18:19] op_sel_hi:[1,0]
	v_pk_mul_f32 v[4:5], v[4:5], v[18:19] op_sel_hi:[1,0]
	v_cvt_pk_bf16_f32 v12, v12, v13
	v_cvt_pk_bf16_f32 v13, v22, v23
	v_mov_b32_e32 v200, v10
	v_mov_b32_e32 v201, v11
	v_mov_b32_e32 v202, v12
	v_mov_b32_e32 v203, v13
	v_lshl_add_u64 v[216:217], v[14:15], 0, v[218:219]
	v_pk_mul_f32 v[6:7], v[6:7], v[18:19] op_sel_hi:[1,0]
	v_pk_mul_f32 v[8:9], v[8:9], v[18:19] op_sel_hi:[1,0]
	v_pk_mul_f32 v[10:11], v[132:133], v[4:5]
	v_pk_mul_f32 v[4:5], v[130:131], v[2:3]
	v_pk_mul_f32 v[8:9], v[136:137], v[8:9]
	v_pk_mul_f32 v[6:7], v[134:135], v[6:7]
	s_nop 0
	v_cvt_pk_bf16_f32 v2, v6, v7
	v_cvt_pk_bf16_f32 v3, v8, v9
	v_cvt_pk_bf16_f32 v4, v4, v5
	v_cvt_pk_bf16_f32 v5, v10, v11
	v_mov_b32_dpp v212, v200 quad_perm:[1,0,3,2] row_mask:0xf bank_mask:0xf
	v_mov_b32_dpp v213, v201 quad_perm:[1,0,3,2] row_mask:0xf bank_mask:0xf
	v_mov_b32_dpp v214, v202 quad_perm:[1,0,3,2] row_mask:0xf bank_mask:0xf
	v_mov_b32_dpp v215, v203 quad_perm:[1,0,3,2] row_mask:0xf bank_mask:0xf
	v_mov_b32_dpp v204, v2 quad_perm:[1,0,3,2] row_mask:0xf bank_mask:0xf
	v_mov_b32_dpp v205, v3 quad_perm:[1,0,3,2] row_mask:0xf bank_mask:0xf
	v_mov_b32_dpp v206, v4 quad_perm:[1,0,3,2] row_mask:0xf bank_mask:0xf
	v_mov_b32_dpp v207, v5 quad_perm:[1,0,3,2] row_mask:0xf bank_mask:0xf
	v_cndmask_b32_e64 v212, v2, v212, s[4:5]
	v_cndmask_b32_e64 v213, v3, v213, s[4:5]
	v_cndmask_b32_e64 v214, v4, v214, s[4:5]
	v_cndmask_b32_e64 v215, v5, v215, s[4:5]
	v_cndmask_b32_e64 v208, v204, v200, s[4:5]
	v_cndmask_b32_e64 v209, v205, v201, s[4:5]
	v_cndmask_b32_e64 v210, v206, v202, s[4:5]
	v_cndmask_b32_e64 v211, v207, v203, s[4:5]
	global_store_dwordx4 v[216:217], v[208:211], off nt
	global_store_dwordx4 v[216:217], v[212:215], off offset:1024 nt
	s_andn2_b64 vcc, exec, s[0:1]
	s_mov_b64 s[0:1], -1
	s_cbranch_vccnz .LBB0_158
